# v20 + hand-written residual epilogues of the out-projection and down GEMMs (residual loads issued ahead of the stores, half the instructions)
# baseline (speedup 1.0000x reference)
; __device__ __forceinline__ unsigned pk2(float lo, float hi) { unsigned r; asm("v_cvt_pk_bf16_f32 %0, %1, %2" : "=v"(r) : "v"(lo), "v"(hi)); return r; }
;     __device__ __forceinline__ void operator()(const f32x4 (&acc)[2][2][4][2], const Unit& u, int wr, int wc, int fr_, int fq_) const {
;         int fr = fr_, fq = fq_; asm volatile("" : "+v"(fr), "+v"(fq));
;         const int row0 = u.pm * BM + wr * 64 + fr, v = vec_of_panel(u.pm);
;         const int colb = u.pn * BM + wc * 32 + 8 * fq;
;         f32x4 gt[2][2], gn[2][2];
; #pragma unroll
;         for (int bj = 0; bj < 2; ++bj)
; #pragma unroll
;             for (int n = 0; n < 2; ++n) { gt[bj][n] = *(const f32x4*)(gate + (size_t)v * 6 * D + colb + bj * HALF + 4 * n);
;                 gn[bj][n] = gnext ? *(const f32x4*)(gnext + (size_t)v * D + colb + bj * HALF + 4 * n) : (f32x4){0.f, 0.f, 0.f, 0.f}; }
; #pragma unroll
;         for (int ai = 0; ai < 2; ++ai)
; #pragma unroll
;             for (int m = 0; m < 4; ++m) { const int row = row0 + ai * HALF + m * 16;
;                 const size_t eo = (size_t)row * D + colb; float s = 0.f;
; #pragma unroll
;                 for (int bj = 0; bj < 2; ++bj) { f32x4 x[2];
;                     if (Xin) { x[0] = *(const f32x4*)(Xin + eo + bj * HALF); x[1] = *(const f32x4*)(Xin + eo + bj * HALF + 4); }
;                     else { const u32x4 xw = *(const u32x4*)(Xb + eo + bj * HALF); x[0] = (f32x4){bf_lo(xw.x), bf_hi(xw.x), bf_lo(xw.y), bf_hi(xw.y)}; x[1] = (f32x4){bf_lo(xw.z), bf_hi(xw.z), bf_lo(xw.w), bf_hi(xw.w)}; }
; #pragma unroll
;                     for (int n = 0; n < 2; ++n) { x[n] = x[n] + gt[bj][n] * acc[ai][bj][m][n];
;                         s += (x[n][0] * x[n][0] + x[n][1] * x[n][1]) + (x[n][2] * x[n][2] + x[n][3] * x[n][3]); }
;                     if (live) { u32x4 xo; xo.x = pk2(x[0][0], x[0][1]); xo.y = pk2(x[0][2], x[0][3]); xo.z = pk2(x[1][0], x[1][1]); xo.w = pk2(x[1][2], x[1][3]); *(u32x4*)(X + eo + bj * HALF) = xo; }
;                     if (gnext && live) { const f32x4 a = x[0] * gn[bj][0], b = x[1] * gn[bj][1];
;                         u32x4 w; w.x = pk2(a[0], a[1]); w.y = pk2(a[2], a[3]); w.z = pk2(b[0], b[1]); w.w = pk2(b[2], b[3]);
;                         *(u32x4*)(AN + (size_t)row * D + colb + bj * HALF) = w; } }
.LBB0_904:
	v_readlane_b32 s12, v253, 3
	v_readlane_b32 s13, v253, 4
	v_readlane_b32 s24, v255, 28
	s_lshl_b32 s4, s94, 8
	s_add_u32 s4, s4, s71
	v_add_u32_e32 v244, s4, v196
	s_nop 0
	s_load_dwordx2 s[38:39], s[12:13], 0xd8
	s_load_dwordx2 s[40:41], s[12:13], 0x0
	s_lshl_b32 s7, s73, 8
	s_add_u32 s7, s7, s77
	v_lshl_add_u32 v243, v194, 3, s7
	v_lshl_add_u32 v249, v244, 11, v243
	s_cmp_ge_u32 s94, 16
	s_cselect_b32 s14, 1, 0
	s_mul_i32 s16, s24, 0x6000
	s_mul_i32 s4, s14, 0xc000
	s_add_u32 s16, s16, s4
	s_add_u32 s16, s16, 0x15aa4000
	v_lshlrev_b32_e32 v248, 2, v243
	v_add_u32_e32 v248, s16, v248
	s_mul_i32 s16, s24, 0x2000
	s_mul_i32 s4, s14, 0x2000
	s_add_u32 s16, s16, s4
	s_add_u32 s16, s16, 0x15b7e000
	v_lshlrev_b32_e32 v247, 2, v243
	v_add_u32_e32 v247, s16, v247
	s_mov_b32 s22, 1
	v_xor_b32_e32 v246, 16, v201
	v_lshlrev_b32_e32 v246, 2, v246
	v_xor_b32_e32 v245, 32, v201
	v_lshlrev_b32_e32 v245, 2, v245
	s_waitcnt lgkmcnt(0)
	global_load_dwordx4 v[42:45], v248, s[38:39]
	global_load_dwordx4 v[46:49], v248, s[38:39] offset:16
	global_load_dwordx4 v[50:53], v248, s[38:39] offset:512
	global_load_dwordx4 v[54:57], v248, s[38:39] offset:528
	global_load_dwordx4 v[62:65], v247, s[38:39]
	global_load_dwordx4 v[70:73], v247, s[38:39] offset:16
	global_load_dwordx4 v[74:77], v247, s[38:39] offset:512
	global_load_dwordx4 v[78:81], v247, s[38:39] offset:528
	s_cmp_lg_u32 s24, 0
	s_cbranch_scc1 .Lp3_bf16
	v_lshlrev_b32_e32 v242, 2, v249
	v_lshlrev_b32_e32 v249, 1, v249
	v_add_u32_e32 v249, 0x100000, v249
	global_load_dwordx4 v[164:167], v242, s[40:41]
	global_load_dwordx4 v[168:171], v242, s[40:41] offset:16
	global_load_dwordx4 v[184:187], v242, s[40:41] offset:512
	global_load_dwordx4 v[202:205], v242, s[40:41] offset:528
	v_add_u32_e32 v242, 0x20000, v242
	s_waitcnt vmcnt(3)
	v_mov_b32_e32 v206, v164
	v_mov_b32_e32 v207, v165
	v_mov_b32_e32 v208, v166
	v_mov_b32_e32 v209, v167
	s_waitcnt vmcnt(2)
	v_mov_b32_e32 v210, v168
	v_mov_b32_e32 v211, v169
	v_mov_b32_e32 v212, v170
	v_mov_b32_e32 v213, v171
	s_waitcnt vmcnt(1)
	v_mov_b32_e32 v214, v184
	v_mov_b32_e32 v215, v185
	v_mov_b32_e32 v216, v186
	v_mov_b32_e32 v217, v187
	s_waitcnt vmcnt(0)
	v_mov_b32_e32 v218, v202
	v_mov_b32_e32 v219, v203
	v_mov_b32_e32 v220, v204
	v_mov_b32_e32 v221, v205
	global_load_dwordx4 v[164:167], v242, s[40:41]
	global_load_dwordx4 v[168:171], v242, s[40:41] offset:16
	global_load_dwordx4 v[184:187], v242, s[40:41] offset:512
	global_load_dwordx4 v[202:205], v242, s[40:41] offset:528
	v_add_u32_e32 v242, 0x20000, v242
	v_pk_fma_f32 v[206:207], v[42:43], v[158:159], v[206:207]
	v_pk_fma_f32 v[208:209], v[44:45], v[160:161], v[208:209]
	v_pk_fma_f32 v[210:211], v[46:47], v[154:155], v[210:211]
	v_pk_fma_f32 v[212:213], v[48:49], v[156:157], v[212:213]
	v_pk_fma_f32 v[214:215], v[50:51], v[150:151], v[214:215]
	v_pk_fma_f32 v[216:217], v[52:53], v[152:153], v[216:217]
	v_pk_fma_f32 v[218:219], v[54:55], v[146:147], v[218:219]
	v_pk_fma_f32 v[220:221], v[56:57], v[148:149], v[220:221]
	v_pk_mul_f32 v[172:173], v[206:207], v[206:207]
	v_pk_fma_f32 v[172:173], v[208:209], v[208:209], v[172:173]
	v_pk_fma_f32 v[172:173], v[210:211], v[210:211], v[172:173]
	v_pk_fma_f32 v[172:173], v[212:213], v[212:213], v[172:173]
	v_pk_fma_f32 v[172:173], v[214:215], v[214:215], v[172:173]
	v_pk_fma_f32 v[172:173], v[216:217], v[216:217], v[172:173]
	v_pk_fma_f32 v[172:173], v[218:219], v[218:219], v[172:173]
	v_pk_fma_f32 v[172:173], v[220:221], v[220:221], v[172:173]
	v_add_f32_e32 v190, v172, v173
	v_cvt_pk_bf16_f32 v222, v206, v207
	v_cvt_pk_bf16_f32 v223, v208, v209
	v_cvt_pk_bf16_f32 v224, v210, v211
	v_cvt_pk_bf16_f32 v225, v212, v213
	global_store_dwordx4 v249, v[222:225], s[38:39]
	v_cvt_pk_bf16_f32 v228, v214, v215
	v_cvt_pk_bf16_f32 v229, v216, v217
	v_cvt_pk_bf16_f32 v230, v218, v219
	v_cvt_pk_bf16_f32 v231, v220, v221
	global_store_dwordx4 v249, v[228:231], s[38:39] offset:256
	s_cmp_eq_u32 s22, 0
	s_cbranch_scc1 .Lp3_noan_1_0
	v_pk_mul_f32 v[206:207], v[206:207], v[62:63]
	v_pk_mul_f32 v[208:209], v[208:209], v[64:65]
	v_pk_mul_f32 v[210:211], v[210:211], v[70:71]
	v_pk_mul_f32 v[212:213], v[212:213], v[72:73]
	v_cvt_pk_bf16_f32 v222, v206, v207
	v_cvt_pk_bf16_f32 v223, v208, v209
	v_cvt_pk_bf16_f32 v224, v210, v211
	v_cvt_pk_bf16_f32 v225, v212, v213
	v_pk_mul_f32 v[214:215], v[214:215], v[74:75]
	v_pk_mul_f32 v[216:217], v[216:217], v[76:77]
	v_pk_mul_f32 v[218:219], v[218:219], v[78:79]
	v_pk_mul_f32 v[220:221], v[220:221], v[80:81]
	v_cvt_pk_bf16_f32 v228, v214, v215
	v_cvt_pk_bf16_f32 v229, v216, v217
	v_cvt_pk_bf16_f32 v230, v218, v219
	v_cvt_pk_bf16_f32 v231, v220, v221
	v_add_u32_e32 v243, 0x4400000, v249
	global_store_dwordx4 v243, v[222:225], s[38:39]
	global_store_dwordx4 v243, v[228:231], s[38:39] offset:256
; __device__ __forceinline__ unsigned pk2(float lo, float hi) { unsigned r; asm("v_cvt_pk_bf16_f32 %0, %1, %2" : "=v"(r) : "v"(lo), "v"(hi)); return r; }
;     __device__ __forceinline__ void operator()(const f32x4 (&acc)[2][2][4][2], const Unit& u, int wr, int wc, int fr_, int fq_) const {
;     ...
;         for (int ai = 0; ai < 2; ++ai)
; #pragma unroll
;             for (int m = 0; m < 4; ++m) { const int row = row0 + ai * HALF + m * 16;
;                 const size_t eo = (size_t)row * D + colb; float s = 0.f;
; #pragma unroll
;                 for (int bj = 0; bj < 2; ++bj) { f32x4 x[2];
;                     if (Xin) { x[0] = *(const f32x4*)(Xin + eo + bj * HALF); x[1] = *(const f32x4*)(Xin + eo + bj * HALF + 4); }
;                     else { const u32x4 xw = *(const u32x4*)(Xb + eo + bj * HALF); x[0] = (f32x4){bf_lo(xw.x), bf_hi(xw.x), bf_lo(xw.y), bf_hi(xw.y)}; x[1] = (f32x4){bf_lo(xw.z), bf_hi(xw.z), bf_lo(xw.w), bf_hi(xw.w)}; }
; #pragma unroll
;                     for (int n = 0; n < 2; ++n) { x[n] = x[n] + gt[bj][n] * acc[ai][bj][m][n];
;                         s += (x[n][0] * x[n][0] + x[n][1] * x[n][1]) + (x[n][2] * x[n][2] + x[n][3] * x[n][3]); }
;                     if (live) { u32x4 xo; xo.x = pk2(x[0][0], x[0][1]); xo.y = pk2(x[0][2], x[0][3]); xo.z = pk2(x[1][0], x[1][1]); xo.w = pk2(x[1][2], x[1][3]); *(u32x4*)(X + eo + bj * HALF) = xo; }
;                     if (gnext && live) { const f32x4 a = x[0] * gn[bj][0], b = x[1] * gn[bj][1];
;                         u32x4 w; w.x = pk2(a[0], a[1]); w.y = pk2(a[2], a[3]); w.z = pk2(b[0], b[1]); w.w = pk2(b[2], b[3]);
;                         *(u32x4*)(AN + (size_t)row * D + colb + bj * HALF) = w; } }
.Lp3_noan_1_0:
	v_add_u32_e32 v249, 0x10000, v249
	s_waitcnt vmcnt(5)
	v_mov_b32_e32 v206, v164
	v_mov_b32_e32 v207, v165
	v_mov_b32_e32 v208, v166
	v_mov_b32_e32 v209, v167
	s_waitcnt vmcnt(4)
	v_mov_b32_e32 v210, v168
	v_mov_b32_e32 v211, v169
	v_mov_b32_e32 v212, v170
	v_mov_b32_e32 v213, v171
	s_waitcnt vmcnt(3)
	v_mov_b32_e32 v214, v184
	v_mov_b32_e32 v215, v185
	v_mov_b32_e32 v216, v186
	v_mov_b32_e32 v217, v187
	s_waitcnt vmcnt(2)
	v_mov_b32_e32 v218, v202
	v_mov_b32_e32 v219, v203
	v_mov_b32_e32 v220, v204
	v_mov_b32_e32 v221, v205
	global_load_dwordx4 v[164:167], v242, s[40:41]
	global_load_dwordx4 v[168:171], v242, s[40:41] offset:16
	global_load_dwordx4 v[184:187], v242, s[40:41] offset:512
	global_load_dwordx4 v[202:205], v242, s[40:41] offset:528
	v_add_u32_e32 v242, 0x20000, v242
	v_pk_fma_f32 v[206:207], v[42:43], v[142:143], v[206:207]
	v_pk_fma_f32 v[208:209], v[44:45], v[144:145], v[208:209]
	v_pk_fma_f32 v[210:211], v[46:47], v[138:139], v[210:211]
	v_pk_fma_f32 v[212:213], v[48:49], v[140:141], v[212:213]
	v_pk_fma_f32 v[214:215], v[50:51], v[134:135], v[214:215]
	v_pk_fma_f32 v[216:217], v[52:53], v[136:137], v[216:217]
	v_pk_fma_f32 v[218:219], v[54:55], v[130:131], v[218:219]
	v_pk_fma_f32 v[220:221], v[56:57], v[132:133], v[220:221]
	v_pk_mul_f32 v[172:173], v[206:207], v[206:207]
	v_pk_fma_f32 v[172:173], v[208:209], v[208:209], v[172:173]
	v_pk_fma_f32 v[172:173], v[210:211], v[210:211], v[172:173]
	v_pk_fma_f32 v[172:173], v[212:213], v[212:213], v[172:173]
	v_pk_fma_f32 v[172:173], v[214:215], v[214:215], v[172:173]
	v_pk_fma_f32 v[172:173], v[216:217], v[216:217], v[172:173]
	v_pk_fma_f32 v[172:173], v[218:219], v[218:219], v[172:173]
	v_pk_fma_f32 v[172:173], v[220:221], v[220:221], v[172:173]
	v_add_f32_e32 v192, v172, v173
	v_cvt_pk_bf16_f32 v222, v206, v207
	v_cvt_pk_bf16_f32 v223, v208, v209
	v_cvt_pk_bf16_f32 v224, v210, v211
	v_cvt_pk_bf16_f32 v225, v212, v213
	global_store_dwordx4 v249, v[222:225], s[38:39]
	v_cvt_pk_bf16_f32 v228, v214, v215
	v_cvt_pk_bf16_f32 v229, v216, v217
	v_cvt_pk_bf16_f32 v230, v218, v219
	v_cvt_pk_bf16_f32 v231, v220, v221
	global_store_dwordx4 v249, v[228:231], s[38:39] offset:256
	s_cmp_eq_u32 s22, 0
	s_cbranch_scc1 .Lp3_noan_1_1
	v_pk_mul_f32 v[206:207], v[206:207], v[62:63]
	v_pk_mul_f32 v[208:209], v[208:209], v[64:65]
	v_pk_mul_f32 v[210:211], v[210:211], v[70:71]
	v_pk_mul_f32 v[212:213], v[212:213], v[72:73]
	v_cvt_pk_bf16_f32 v222, v206, v207
	v_cvt_pk_bf16_f32 v223, v208, v209
	v_cvt_pk_bf16_f32 v224, v210, v211
	v_cvt_pk_bf16_f32 v225, v212, v213
	v_pk_mul_f32 v[214:215], v[214:215], v[74:75]
	v_pk_mul_f32 v[216:217], v[216:217], v[76:77]
	v_pk_mul_f32 v[218:219], v[218:219], v[78:79]
	v_pk_mul_f32 v[220:221], v[220:221], v[80:81]
	v_cvt_pk_bf16_f32 v228, v214, v215
	v_cvt_pk_bf16_f32 v229, v216, v217
	v_cvt_pk_bf16_f32 v230, v218, v219
	v_cvt_pk_bf16_f32 v231, v220, v221
	v_add_u32_e32 v243, 0x4400000, v249
	global_store_dwordx4 v243, v[222:225], s[38:39]
	global_store_dwordx4 v243, v[228:231], s[38:39] offset:256
.Lp3_noan_1_1:
	v_add_u32_e32 v249, 0x10000, v249
	s_waitcnt vmcnt(5)
	v_mov_b32_e32 v206, v164
	v_mov_b32_e32 v207, v165
	v_mov_b32_e32 v208, v166
	v_mov_b32_e32 v209, v167
	s_waitcnt vmcnt(4)
	v_mov_b32_e32 v210, v168
	v_mov_b32_e32 v211, v169
	v_mov_b32_e32 v212, v170
	v_mov_b32_e32 v213, v171
	s_waitcnt vmcnt(3)
	v_mov_b32_e32 v214, v184
	v_mov_b32_e32 v215, v185
	v_mov_b32_e32 v216, v186
	v_mov_b32_e32 v217, v187
	s_waitcnt vmcnt(2)
	v_mov_b32_e32 v218, v202
	v_mov_b32_e32 v219, v203
	v_mov_b32_e32 v220, v204
	v_mov_b32_e32 v221, v205
	global_load_dwordx4 v[164:167], v242, s[40:41]
	global_load_dwordx4 v[168:171], v242, s[40:41] offset:16
	global_load_dwordx4 v[184:187], v242, s[40:41] offset:512
	global_load_dwordx4 v[202:205], v242, s[40:41] offset:528
	v_add_u32_e32 v242, 0xa0000, v242
	v_pk_fma_f32 v[206:207], v[42:43], v[126:127], v[206:207]
	v_pk_fma_f32 v[208:209], v[44:45], v[128:129], v[208:209]
	v_pk_fma_f32 v[210:211], v[46:47], v[122:123], v[210:211]
	v_pk_fma_f32 v[212:213], v[48:49], v[124:125], v[212:213]
	v_pk_fma_f32 v[214:215], v[50:51], v[118:119], v[214:215]
	v_pk_fma_f32 v[216:217], v[52:53], v[120:121], v[216:217]
	v_pk_fma_f32 v[218:219], v[54:55], v[114:115], v[218:219]
	v_pk_fma_f32 v[220:221], v[56:57], v[116:117], v[220:221]
	v_pk_mul_f32 v[172:173], v[206:207], v[206:207]
	v_pk_fma_f32 v[172:173], v[208:209], v[208:209], v[172:173]
	v_pk_fma_f32 v[172:173], v[210:211], v[210:211], v[172:173]
	v_pk_fma_f32 v[172:173], v[212:213], v[212:213], v[172:173]
	v_pk_fma_f32 v[172:173], v[214:215], v[214:215], v[172:173]
	v_pk_fma_f32 v[172:173], v[216:217], v[216:217], v[172:173]
	v_pk_fma_f32 v[172:173], v[218:219], v[218:219], v[172:173]
	v_pk_fma_f32 v[172:173], v[220:221], v[220:221], v[172:173]
	v_add_f32_e32 v226, v172, v173
	v_cvt_pk_bf16_f32 v222, v206, v207
	v_cvt_pk_bf16_f32 v223, v208, v209
	v_cvt_pk_bf16_f32 v224, v210, v211
	v_cvt_pk_bf16_f32 v225, v212, v213
	global_store_dwordx4 v249, v[222:225], s[38:39]
	v_cvt_pk_bf16_f32 v228, v214, v215
	v_cvt_pk_bf16_f32 v229, v216, v217
	v_cvt_pk_bf16_f32 v230, v218, v219
	v_cvt_pk_bf16_f32 v231, v220, v221
	global_store_dwordx4 v249, v[228:231], s[38:39] offset:256
	s_cmp_eq_u32 s22, 0
	s_cbranch_scc1 .Lp3_noan_1_2
	v_pk_mul_f32 v[206:207], v[206:207], v[62:63]
	v_pk_mul_f32 v[208:209], v[208:209], v[64:65]
	v_pk_mul_f32 v[210:211], v[210:211], v[70:71]
	v_pk_mul_f32 v[212:213], v[212:213], v[72:73]
	v_cvt_pk_bf16_f32 v222, v206, v207
	v_cvt_pk_bf16_f32 v223, v208, v209
	v_cvt_pk_bf16_f32 v224, v210, v211
	v_cvt_pk_bf16_f32 v225, v212, v213
	v_pk_mul_f32 v[214:215], v[214:215], v[74:75]
	v_pk_mul_f32 v[216:217], v[216:217], v[76:77]
	v_pk_mul_f32 v[218:219], v[218:219], v[78:79]
	v_pk_mul_f32 v[220:221], v[220:221], v[80:81]
	v_cvt_pk_bf16_f32 v228, v214, v215
	v_cvt_pk_bf16_f32 v229, v216, v217
	v_cvt_pk_bf16_f32 v230, v218, v219
	v_cvt_pk_bf16_f32 v231, v220, v221
	v_add_u32_e32 v243, 0x4400000, v249
	global_store_dwordx4 v243, v[222:225], s[38:39]
	global_store_dwordx4 v243, v[228:231], s[38:39] offset:256
; __device__ __forceinline__ unsigned pk2(float lo, float hi) { unsigned r; asm("v_cvt_pk_bf16_f32 %0, %1, %2" : "=v"(r) : "v"(lo), "v"(hi)); return r; }
;     __device__ __forceinline__ void operator()(const f32x4 (&acc)[2][2][4][2], const Unit& u, int wr, int wc, int fr_, int fq_) const {
;     ...
;         for (int ai = 0; ai < 2; ++ai)
; #pragma unroll
;             for (int m = 0; m < 4; ++m) { const int row = row0 + ai * HALF + m * 16;
;                 const size_t eo = (size_t)row * D + colb; float s = 0.f;
; #pragma unroll
;                 for (int bj = 0; bj < 2; ++bj) { f32x4 x[2];
;                     if (Xin) { x[0] = *(const f32x4*)(Xin + eo + bj * HALF); x[1] = *(const f32x4*)(Xin + eo + bj * HALF + 4); }
;                     else { const u32x4 xw = *(const u32x4*)(Xb + eo + bj * HALF); x[0] = (f32x4){bf_lo(xw.x), bf_hi(xw.x), bf_lo(xw.y), bf_hi(xw.y)}; x[1] = (f32x4){bf_lo(xw.z), bf_hi(xw.z), bf_lo(xw.w), bf_hi(xw.w)}; }
; #pragma unroll
;                     for (int n = 0; n < 2; ++n) { x[n] = x[n] + gt[bj][n] * acc[ai][bj][m][n];
;                         s += (x[n][0] * x[n][0] + x[n][1] * x[n][1]) + (x[n][2] * x[n][2] + x[n][3] * x[n][3]); }
;                     if (live) { u32x4 xo; xo.x = pk2(x[0][0], x[0][1]); xo.y = pk2(x[0][2], x[0][3]); xo.z = pk2(x[1][0], x[1][1]); xo.w = pk2(x[1][2], x[1][3]); *(u32x4*)(X + eo + bj * HALF) = xo; }
;                     if (gnext && live) { const f32x4 a = x[0] * gn[bj][0], b = x[1] * gn[bj][1];
;                         u32x4 w; w.x = pk2(a[0], a[1]); w.y = pk2(a[2], a[3]); w.z = pk2(b[0], b[1]); w.w = pk2(b[2], b[3]);
;                         *(u32x4*)(AN + (size_t)row * D + colb + bj * HALF) = w; } }
.Lp3_noan_1_2:
	v_add_u32_e32 v249, 0x10000, v249
	s_waitcnt vmcnt(5)
	v_mov_b32_e32 v206, v164
	v_mov_b32_e32 v207, v165
	v_mov_b32_e32 v208, v166
	v_mov_b32_e32 v209, v167
	s_waitcnt vmcnt(4)
	v_mov_b32_e32 v210, v168
	v_mov_b32_e32 v211, v169
	v_mov_b32_e32 v212, v170
	v_mov_b32_e32 v213, v171
	s_waitcnt vmcnt(3)
	v_mov_b32_e32 v214, v184
	v_mov_b32_e32 v215, v185
	v_mov_b32_e32 v216, v186
	v_mov_b32_e32 v217, v187
	s_waitcnt vmcnt(2)
	v_mov_b32_e32 v218, v202
	v_mov_b32_e32 v219, v203
	v_mov_b32_e32 v220, v204
	v_mov_b32_e32 v221, v205
	global_load_dwordx4 v[164:167], v242, s[40:41]
	global_load_dwordx4 v[168:171], v242, s[40:41] offset:16
	global_load_dwordx4 v[184:187], v242, s[40:41] offset:512
	global_load_dwordx4 v[202:205], v242, s[40:41] offset:528
	v_add_u32_e32 v242, 0x20000, v242
	v_pk_fma_f32 v[206:207], v[42:43], v[110:111], v[206:207]
	v_pk_fma_f32 v[208:209], v[44:45], v[112:113], v[208:209]
	v_pk_fma_f32 v[210:211], v[46:47], v[106:107], v[210:211]
	v_pk_fma_f32 v[212:213], v[48:49], v[108:109], v[212:213]
	v_pk_fma_f32 v[214:215], v[50:51], v[102:103], v[214:215]
	v_pk_fma_f32 v[216:217], v[52:53], v[104:105], v[216:217]
	v_pk_fma_f32 v[218:219], v[54:55], v[98:99], v[218:219]
	v_pk_fma_f32 v[220:221], v[56:57], v[100:101], v[220:221]
	v_pk_mul_f32 v[172:173], v[206:207], v[206:207]
	v_pk_fma_f32 v[172:173], v[208:209], v[208:209], v[172:173]
	v_pk_fma_f32 v[172:173], v[210:211], v[210:211], v[172:173]
	v_pk_fma_f32 v[172:173], v[212:213], v[212:213], v[172:173]
	v_pk_fma_f32 v[172:173], v[214:215], v[214:215], v[172:173]
	v_pk_fma_f32 v[172:173], v[216:217], v[216:217], v[172:173]
	v_pk_fma_f32 v[172:173], v[218:219], v[218:219], v[172:173]
	v_pk_fma_f32 v[172:173], v[220:221], v[220:221], v[172:173]
	v_add_f32_e32 v236, v172, v173
	v_cvt_pk_bf16_f32 v222, v206, v207
	v_cvt_pk_bf16_f32 v223, v208, v209
	v_cvt_pk_bf16_f32 v224, v210, v211
	v_cvt_pk_bf16_f32 v225, v212, v213
	global_store_dwordx4 v249, v[222:225], s[38:39]
	v_cvt_pk_bf16_f32 v228, v214, v215
	v_cvt_pk_bf16_f32 v229, v216, v217
	v_cvt_pk_bf16_f32 v230, v218, v219
	v_cvt_pk_bf16_f32 v231, v220, v221
	global_store_dwordx4 v249, v[228:231], s[38:39] offset:256
	s_cmp_eq_u32 s22, 0
	s_cbranch_scc1 .Lp3_noan_1_3
	v_pk_mul_f32 v[206:207], v[206:207], v[62:63]
	v_pk_mul_f32 v[208:209], v[208:209], v[64:65]
	v_pk_mul_f32 v[210:211], v[210:211], v[70:71]
	v_pk_mul_f32 v[212:213], v[212:213], v[72:73]
	v_cvt_pk_bf16_f32 v222, v206, v207
	v_cvt_pk_bf16_f32 v223, v208, v209
	v_cvt_pk_bf16_f32 v224, v210, v211
	v_cvt_pk_bf16_f32 v225, v212, v213
	v_pk_mul_f32 v[214:215], v[214:215], v[74:75]
	v_pk_mul_f32 v[216:217], v[216:217], v[76:77]
	v_pk_mul_f32 v[218:219], v[218:219], v[78:79]
	v_pk_mul_f32 v[220:221], v[220:221], v[80:81]
	v_cvt_pk_bf16_f32 v228, v214, v215
	v_cvt_pk_bf16_f32 v229, v216, v217
	v_cvt_pk_bf16_f32 v230, v218, v219
	v_cvt_pk_bf16_f32 v231, v220, v221
	v_add_u32_e32 v243, 0x4400000, v249
	global_store_dwordx4 v243, v[222:225], s[38:39]
	global_store_dwordx4 v243, v[228:231], s[38:39] offset:256
.Lp3_noan_1_3:
	v_add_u32_e32 v249, 0x50000, v249
	s_waitcnt vmcnt(5)
	v_mov_b32_e32 v206, v164
	v_mov_b32_e32 v207, v165
	v_mov_b32_e32 v208, v166
	v_mov_b32_e32 v209, v167
	s_waitcnt vmcnt(4)
	v_mov_b32_e32 v210, v168
	v_mov_b32_e32 v211, v169
	v_mov_b32_e32 v212, v170
	v_mov_b32_e32 v213, v171
	s_waitcnt vmcnt(3)
	v_mov_b32_e32 v214, v184
	v_mov_b32_e32 v215, v185
	v_mov_b32_e32 v216, v186
	v_mov_b32_e32 v217, v187
	s_waitcnt vmcnt(2)
	v_mov_b32_e32 v218, v202
	v_mov_b32_e32 v219, v203
	v_mov_b32_e32 v220, v204
	v_mov_b32_e32 v221, v205
	global_load_dwordx4 v[164:167], v242, s[40:41]
	global_load_dwordx4 v[168:171], v242, s[40:41] offset:16
	global_load_dwordx4 v[184:187], v242, s[40:41] offset:512
	global_load_dwordx4 v[202:205], v242, s[40:41] offset:528
	v_add_u32_e32 v242, 0x20000, v242
	v_pk_fma_f32 v[206:207], v[42:43], v[94:95], v[206:207]
	v_pk_fma_f32 v[208:209], v[44:45], v[96:97], v[208:209]
	v_pk_fma_f32 v[210:211], v[46:47], v[90:91], v[210:211]
	v_pk_fma_f32 v[212:213], v[48:49], v[92:93], v[212:213]
	v_pk_fma_f32 v[214:215], v[50:51], v[86:87], v[214:215]
	v_pk_fma_f32 v[216:217], v[52:53], v[88:89], v[216:217]
	v_pk_fma_f32 v[218:219], v[54:55], v[82:83], v[218:219]
	v_pk_fma_f32 v[220:221], v[56:57], v[84:85], v[220:221]
	v_pk_mul_f32 v[172:173], v[206:207], v[206:207]
	v_pk_fma_f32 v[172:173], v[208:209], v[208:209], v[172:173]
	v_pk_fma_f32 v[172:173], v[210:211], v[210:211], v[172:173]
	v_pk_fma_f32 v[172:173], v[212:213], v[212:213], v[172:173]
	v_pk_fma_f32 v[172:173], v[214:215], v[214:215], v[172:173]
	v_pk_fma_f32 v[172:173], v[216:217], v[216:217], v[172:173]
	v_pk_fma_f32 v[172:173], v[218:219], v[218:219], v[172:173]
	v_pk_fma_f32 v[172:173], v[220:221], v[220:221], v[172:173]
	v_add_f32_e32 v239, v172, v173
	v_cvt_pk_bf16_f32 v222, v206, v207
	v_cvt_pk_bf16_f32 v223, v208, v209
	v_cvt_pk_bf16_f32 v224, v210, v211
	v_cvt_pk_bf16_f32 v225, v212, v213
	global_store_dwordx4 v249, v[222:225], s[38:39]
	v_cvt_pk_bf16_f32 v228, v214, v215
	v_cvt_pk_bf16_f32 v229, v216, v217
	v_cvt_pk_bf16_f32 v230, v218, v219
	v_cvt_pk_bf16_f32 v231, v220, v221
	global_store_dwordx4 v249, v[228:231], s[38:39] offset:256
	s_cmp_eq_u32 s22, 0
	s_cbranch_scc1 .Lp3_noan_1_4
	v_pk_mul_f32 v[206:207], v[206:207], v[62:63]
	v_pk_mul_f32 v[208:209], v[208:209], v[64:65]
	v_pk_mul_f32 v[210:211], v[210:211], v[70:71]
	v_pk_mul_f32 v[212:213], v[212:213], v[72:73]
	v_cvt_pk_bf16_f32 v222, v206, v207
	v_cvt_pk_bf16_f32 v223, v208, v209
	v_cvt_pk_bf16_f32 v224, v210, v211
	v_cvt_pk_bf16_f32 v225, v212, v213
	v_pk_mul_f32 v[214:215], v[214:215], v[74:75]
	v_pk_mul_f32 v[216:217], v[216:217], v[76:77]
	v_pk_mul_f32 v[218:219], v[218:219], v[78:79]
	v_pk_mul_f32 v[220:221], v[220:221], v[80:81]
	v_cvt_pk_bf16_f32 v228, v214, v215
	v_cvt_pk_bf16_f32 v229, v216, v217
	v_cvt_pk_bf16_f32 v230, v218, v219
	v_cvt_pk_bf16_f32 v231, v220, v221
	v_add_u32_e32 v243, 0x4400000, v249
	global_store_dwordx4 v243, v[222:225], s[38:39]
	global_store_dwordx4 v243, v[228:231], s[38:39] offset:256
; __device__ __forceinline__ unsigned pk2(float lo, float hi) { unsigned r; asm("v_cvt_pk_bf16_f32 %0, %1, %2" : "=v"(r) : "v"(lo), "v"(hi)); return r; }
;     __device__ __forceinline__ void operator()(const f32x4 (&acc)[2][2][4][2], const Unit& u, int wr, int wc, int fr_, int fq_) const {
;     ...
;         for (int ai = 0; ai < 2; ++ai)
; #pragma unroll
;             for (int m = 0; m < 4; ++m) { const int row = row0 + ai * HALF + m * 16;
;                 const size_t eo = (size_t)row * D + colb; float s = 0.f;
; #pragma unroll
;                 for (int bj = 0; bj < 2; ++bj) { f32x4 x[2];
;                     if (Xin) { x[0] = *(const f32x4*)(Xin + eo + bj * HALF); x[1] = *(const f32x4*)(Xin + eo + bj * HALF + 4); }
;                     else { const u32x4 xw = *(const u32x4*)(Xb + eo + bj * HALF); x[0] = (f32x4){bf_lo(xw.x), bf_hi(xw.x), bf_lo(xw.y), bf_hi(xw.y)}; x[1] = (f32x4){bf_lo(xw.z), bf_hi(xw.z), bf_lo(xw.w), bf_hi(xw.w)}; }
; #pragma unroll
;                     for (int n = 0; n < 2; ++n) { x[n] = x[n] + gt[bj][n] * acc[ai][bj][m][n];
;                         s += (x[n][0] * x[n][0] + x[n][1] * x[n][1]) + (x[n][2] * x[n][2] + x[n][3] * x[n][3]); }
;                     if (live) { u32x4 xo; xo.x = pk2(x[0][0], x[0][1]); xo.y = pk2(x[0][2], x[0][3]); xo.z = pk2(x[1][0], x[1][1]); xo.w = pk2(x[1][2], x[1][3]); *(u32x4*)(X + eo + bj * HALF) = xo; }
;                     if (gnext && live) { const f32x4 a = x[0] * gn[bj][0], b = x[1] * gn[bj][1];
;                         u32x4 w; w.x = pk2(a[0], a[1]); w.y = pk2(a[2], a[3]); w.z = pk2(b[0], b[1]); w.w = pk2(b[2], b[3]);
;                         *(u32x4*)(AN + (size_t)row * D + colb + bj * HALF) = w; } }
.Lp3_noan_1_4:
	v_add_u32_e32 v249, 0x10000, v249
	s_waitcnt vmcnt(5)
	v_mov_b32_e32 v206, v164
	v_mov_b32_e32 v207, v165
	v_mov_b32_e32 v208, v166
	v_mov_b32_e32 v209, v167
	s_waitcnt vmcnt(4)
	v_mov_b32_e32 v210, v168
	v_mov_b32_e32 v211, v169
	v_mov_b32_e32 v212, v170
	v_mov_b32_e32 v213, v171
	s_waitcnt vmcnt(3)
	v_mov_b32_e32 v214, v184
	v_mov_b32_e32 v215, v185
	v_mov_b32_e32 v216, v186
	v_mov_b32_e32 v217, v187
	s_waitcnt vmcnt(2)
	v_mov_b32_e32 v218, v202
	v_mov_b32_e32 v219, v203
	v_mov_b32_e32 v220, v204
	v_mov_b32_e32 v221, v205
	global_load_dwordx4 v[164:167], v242, s[40:41]
	global_load_dwordx4 v[168:171], v242, s[40:41] offset:16
	global_load_dwordx4 v[184:187], v242, s[40:41] offset:512
	global_load_dwordx4 v[202:205], v242, s[40:41] offset:528
	v_add_u32_e32 v242, 0x20000, v242
	v_pk_fma_f32 v[206:207], v[42:43], v[66:67], v[206:207]
	v_pk_fma_f32 v[208:209], v[44:45], v[68:69], v[208:209]
	v_pk_fma_f32 v[210:211], v[46:47], v[58:59], v[210:211]
	v_pk_fma_f32 v[212:213], v[48:49], v[60:61], v[212:213]
	v_pk_fma_f32 v[214:215], v[50:51], v[38:39], v[214:215]
	v_pk_fma_f32 v[216:217], v[52:53], v[40:41], v[216:217]
	v_pk_fma_f32 v[218:219], v[54:55], v[34:35], v[218:219]
	v_pk_fma_f32 v[220:221], v[56:57], v[36:37], v[220:221]
	v_pk_mul_f32 v[172:173], v[206:207], v[206:207]
	v_pk_fma_f32 v[172:173], v[208:209], v[208:209], v[172:173]
	v_pk_fma_f32 v[172:173], v[210:211], v[210:211], v[172:173]
	v_pk_fma_f32 v[172:173], v[212:213], v[212:213], v[172:173]
	v_pk_fma_f32 v[172:173], v[214:215], v[214:215], v[172:173]
	v_pk_fma_f32 v[172:173], v[216:217], v[216:217], v[172:173]
	v_pk_fma_f32 v[172:173], v[218:219], v[218:219], v[172:173]
	v_pk_fma_f32 v[172:173], v[220:221], v[220:221], v[172:173]
	v_add_f32_e32 v252, v172, v173
	v_cvt_pk_bf16_f32 v222, v206, v207
	v_cvt_pk_bf16_f32 v223, v208, v209
	v_cvt_pk_bf16_f32 v224, v210, v211
	v_cvt_pk_bf16_f32 v225, v212, v213
	global_store_dwordx4 v249, v[222:225], s[38:39]
	v_cvt_pk_bf16_f32 v228, v214, v215
	v_cvt_pk_bf16_f32 v229, v216, v217
	v_cvt_pk_bf16_f32 v230, v218, v219
	v_cvt_pk_bf16_f32 v231, v220, v221
	global_store_dwordx4 v249, v[228:231], s[38:39] offset:256
	s_cmp_eq_u32 s22, 0
	s_cbranch_scc1 .Lp3_noan_1_5
	v_pk_mul_f32 v[206:207], v[206:207], v[62:63]
	v_pk_mul_f32 v[208:209], v[208:209], v[64:65]
	v_pk_mul_f32 v[210:211], v[210:211], v[70:71]
	v_pk_mul_f32 v[212:213], v[212:213], v[72:73]
	v_cvt_pk_bf16_f32 v222, v206, v207
	v_cvt_pk_bf16_f32 v223, v208, v209
	v_cvt_pk_bf16_f32 v224, v210, v211
	v_cvt_pk_bf16_f32 v225, v212, v213
	v_pk_mul_f32 v[214:215], v[214:215], v[74:75]
	v_pk_mul_f32 v[216:217], v[216:217], v[76:77]
	v_pk_mul_f32 v[218:219], v[218:219], v[78:79]
	v_pk_mul_f32 v[220:221], v[220:221], v[80:81]
	v_cvt_pk_bf16_f32 v228, v214, v215
	v_cvt_pk_bf16_f32 v229, v216, v217
	v_cvt_pk_bf16_f32 v230, v218, v219
	v_cvt_pk_bf16_f32 v231, v220, v221
	v_add_u32_e32 v243, 0x4400000, v249
	global_store_dwordx4 v243, v[222:225], s[38:39]
	global_store_dwordx4 v243, v[228:231], s[38:39] offset:256
; __device__ __forceinline__ unsigned pk2(float lo, float hi) { unsigned r; asm("v_cvt_pk_bf16_f32 %0, %1, %2" : "=v"(r) : "v"(lo), "v"(hi)); return r; }
;     __device__ __forceinline__ void operator()(const f32x4 (&acc)[2][2][4][2], const Unit& u, int wr, int wc, int fr_, int fq_) const {
;     ...
;         for (int ai = 0; ai < 2; ++ai)
; #pragma unroll
;             for (int m = 0; m < 4; ++m) { const int row = row0 + ai * HALF + m * 16;
;                 const size_t eo = (size_t)row * D + colb; float s = 0.f;
; #pragma unroll
;                 for (int bj = 0; bj < 2; ++bj) { f32x4 x[2];
;                     if (Xin) { x[0] = *(const f32x4*)(Xin + eo + bj * HALF); x[1] = *(const f32x4*)(Xin + eo + bj * HALF + 4); }
;                     else { const u32x4 xw = *(const u32x4*)(Xb + eo + bj * HALF); x[0] = (f32x4){bf_lo(xw.x), bf_hi(xw.x), bf_lo(xw.y), bf_hi(xw.y)}; x[1] = (f32x4){bf_lo(xw.z), bf_hi(xw.z), bf_lo(xw.w), bf_hi(xw.w)}; }
; #pragma unroll
;                     for (int n = 0; n < 2; ++n) { x[n] = x[n] + gt[bj][n] * acc[ai][bj][m][n];
;                         s += (x[n][0] * x[n][0] + x[n][1] * x[n][1]) + (x[n][2] * x[n][2] + x[n][3] * x[n][3]); }
;                     if (live) { u32x4 xo; xo.x = pk2(x[0][0], x[0][1]); xo.y = pk2(x[0][2], x[0][3]); xo.z = pk2(x[1][0], x[1][1]); xo.w = pk2(x[1][2], x[1][3]); *(u32x4*)(X + eo + bj * HALF) = xo; }
;                     if (gnext && live) { const f32x4 a = x[0] * gn[bj][0], b = x[1] * gn[bj][1];
;                         u32x4 w; w.x = pk2(a[0], a[1]); w.y = pk2(a[2], a[3]); w.z = pk2(b[0], b[1]); w.w = pk2(b[2], b[3]);
;                         *(u32x4*)(AN + (size_t)row * D + colb + bj * HALF) = w; } }
.Lp3_noan_1_5:
	v_add_u32_e32 v249, 0x10000, v249
	s_waitcnt vmcnt(5)
	v_mov_b32_e32 v206, v164
	v_mov_b32_e32 v207, v165
	v_mov_b32_e32 v208, v166
	v_mov_b32_e32 v209, v167
	s_waitcnt vmcnt(4)
	v_mov_b32_e32 v210, v168
	v_mov_b32_e32 v211, v169
	v_mov_b32_e32 v212, v170
	v_mov_b32_e32 v213, v171
	s_waitcnt vmcnt(3)
	v_mov_b32_e32 v214, v184
	v_mov_b32_e32 v215, v185
	v_mov_b32_e32 v216, v186
	v_mov_b32_e32 v217, v187
	s_waitcnt vmcnt(2)
	v_mov_b32_e32 v218, v202
	v_mov_b32_e32 v219, v203
	v_mov_b32_e32 v220, v204
	v_mov_b32_e32 v221, v205
	global_load_dwordx4 v[164:167], v242, s[40:41]
	global_load_dwordx4 v[168:171], v242, s[40:41] offset:16
	global_load_dwordx4 v[184:187], v242, s[40:41] offset:512
	global_load_dwordx4 v[202:205], v242, s[40:41] offset:528
	v_pk_fma_f32 v[206:207], v[42:43], v[30:31], v[206:207]
	v_pk_fma_f32 v[208:209], v[44:45], v[32:33], v[208:209]
	v_pk_fma_f32 v[210:211], v[46:47], v[26:27], v[210:211]
	v_pk_fma_f32 v[212:213], v[48:49], v[28:29], v[212:213]
	v_pk_fma_f32 v[214:215], v[50:51], v[22:23], v[214:215]
	v_pk_fma_f32 v[216:217], v[52:53], v[24:25], v[216:217]
	v_pk_fma_f32 v[218:219], v[54:55], v[18:19], v[218:219]
	v_pk_fma_f32 v[220:221], v[56:57], v[20:21], v[220:221]
	v_pk_mul_f32 v[172:173], v[206:207], v[206:207]
	v_pk_fma_f32 v[172:173], v[208:209], v[208:209], v[172:173]
	v_pk_fma_f32 v[172:173], v[210:211], v[210:211], v[172:173]
	v_pk_fma_f32 v[172:173], v[212:213], v[212:213], v[172:173]
	v_pk_fma_f32 v[172:173], v[214:215], v[214:215], v[172:173]
	v_pk_fma_f32 v[172:173], v[216:217], v[216:217], v[172:173]
	v_pk_fma_f32 v[172:173], v[218:219], v[218:219], v[172:173]
	v_pk_fma_f32 v[172:173], v[220:221], v[220:221], v[172:173]
	v_add_f32_e32 v251, v172, v173
	v_cvt_pk_bf16_f32 v222, v206, v207
	v_cvt_pk_bf16_f32 v223, v208, v209
	v_cvt_pk_bf16_f32 v224, v210, v211
	v_cvt_pk_bf16_f32 v225, v212, v213
	global_store_dwordx4 v249, v[222:225], s[38:39]
	v_cvt_pk_bf16_f32 v228, v214, v215
	v_cvt_pk_bf16_f32 v229, v216, v217
	v_cvt_pk_bf16_f32 v230, v218, v219
	v_cvt_pk_bf16_f32 v231, v220, v221
	global_store_dwordx4 v249, v[228:231], s[38:39] offset:256
	s_cmp_eq_u32 s22, 0
	s_cbranch_scc1 .Lp3_noan_1_6
	v_pk_mul_f32 v[206:207], v[206:207], v[62:63]
	v_pk_mul_f32 v[208:209], v[208:209], v[64:65]
	v_pk_mul_f32 v[210:211], v[210:211], v[70:71]
	v_pk_mul_f32 v[212:213], v[212:213], v[72:73]
	v_cvt_pk_bf16_f32 v222, v206, v207
	v_cvt_pk_bf16_f32 v223, v208, v209
	v_cvt_pk_bf16_f32 v224, v210, v211
	v_cvt_pk_bf16_f32 v225, v212, v213
	v_pk_mul_f32 v[214:215], v[214:215], v[74:75]
	v_pk_mul_f32 v[216:217], v[216:217], v[76:77]
	v_pk_mul_f32 v[218:219], v[218:219], v[78:79]
	v_pk_mul_f32 v[220:221], v[220:221], v[80:81]
	v_cvt_pk_bf16_f32 v228, v214, v215
	v_cvt_pk_bf16_f32 v229, v216, v217
	v_cvt_pk_bf16_f32 v230, v218, v219
	v_cvt_pk_bf16_f32 v231, v220, v221
	v_add_u32_e32 v243, 0x4400000, v249
	global_store_dwordx4 v243, v[222:225], s[38:39]
	global_store_dwordx4 v243, v[228:231], s[38:39] offset:256
.Lp3_noan_1_6:
	v_add_u32_e32 v249, 0x10000, v249
	s_waitcnt vmcnt(5)
	v_mov_b32_e32 v206, v164
	v_mov_b32_e32 v207, v165
	v_mov_b32_e32 v208, v166
	v_mov_b32_e32 v209, v167
	s_waitcnt vmcnt(4)
	v_mov_b32_e32 v210, v168
	v_mov_b32_e32 v211, v169
	v_mov_b32_e32 v212, v170
	v_mov_b32_e32 v213, v171
	s_waitcnt vmcnt(3)
	v_mov_b32_e32 v214, v184
	v_mov_b32_e32 v215, v185
	v_mov_b32_e32 v216, v186
	v_mov_b32_e32 v217, v187
	s_waitcnt vmcnt(2)
	v_mov_b32_e32 v218, v202
	v_mov_b32_e32 v219, v203
	v_mov_b32_e32 v220, v204
	v_mov_b32_e32 v221, v205
	v_pk_fma_f32 v[206:207], v[42:43], v[14:15], v[206:207]
	v_pk_fma_f32 v[208:209], v[44:45], v[16:17], v[208:209]
	v_pk_fma_f32 v[210:211], v[46:47], v[10:11], v[210:211]
	v_pk_fma_f32 v[212:213], v[48:49], v[12:13], v[212:213]
	v_pk_fma_f32 v[214:215], v[50:51], v[6:7], v[214:215]
	v_pk_fma_f32 v[216:217], v[52:53], v[8:9], v[216:217]
	v_pk_fma_f32 v[218:219], v[54:55], v[2:3], v[218:219]
	v_pk_fma_f32 v[220:221], v[56:57], v[4:5], v[220:221]
	v_pk_mul_f32 v[172:173], v[206:207], v[206:207]
	v_pk_fma_f32 v[172:173], v[208:209], v[208:209], v[172:173]
	v_pk_fma_f32 v[172:173], v[210:211], v[210:211], v[172:173]
	v_pk_fma_f32 v[172:173], v[212:213], v[212:213], v[172:173]
	v_pk_fma_f32 v[172:173], v[214:215], v[214:215], v[172:173]
	v_pk_fma_f32 v[172:173], v[216:217], v[216:217], v[172:173]
	v_pk_fma_f32 v[172:173], v[218:219], v[218:219], v[172:173]
	v_pk_fma_f32 v[172:173], v[220:221], v[220:221], v[172:173]
	v_add_f32_e32 v250, v172, v173
	v_cvt_pk_bf16_f32 v222, v206, v207
	v_cvt_pk_bf16_f32 v223, v208, v209
	v_cvt_pk_bf16_f32 v224, v210, v211
	v_cvt_pk_bf16_f32 v225, v212, v213
	global_store_dwordx4 v249, v[222:225], s[38:39]
	v_cvt_pk_bf16_f32 v228, v214, v215
	v_cvt_pk_bf16_f32 v229, v216, v217
	v_cvt_pk_bf16_f32 v230, v218, v219
	v_cvt_pk_bf16_f32 v231, v220, v221
	global_store_dwordx4 v249, v[228:231], s[38:39] offset:256
	s_cmp_eq_u32 s22, 0
	s_cbranch_scc1 .Lp3_noan_1_7
	v_pk_mul_f32 v[206:207], v[206:207], v[62:63]
	v_pk_mul_f32 v[208:209], v[208:209], v[64:65]
	v_pk_mul_f32 v[210:211], v[210:211], v[70:71]
	v_pk_mul_f32 v[212:213], v[212:213], v[72:73]
	v_cvt_pk_bf16_f32 v222, v206, v207
	v_cvt_pk_bf16_f32 v223, v208, v209
	v_cvt_pk_bf16_f32 v224, v210, v211
	v_cvt_pk_bf16_f32 v225, v212, v213
	v_pk_mul_f32 v[214:215], v[214:215], v[74:75]
	v_pk_mul_f32 v[216:217], v[216:217], v[76:77]
	v_pk_mul_f32 v[218:219], v[218:219], v[78:79]
	v_pk_mul_f32 v[220:221], v[220:221], v[80:81]
	v_cvt_pk_bf16_f32 v228, v214, v215
	v_cvt_pk_bf16_f32 v229, v216, v217
	v_cvt_pk_bf16_f32 v230, v218, v219
	v_cvt_pk_bf16_f32 v231, v220, v221
	v_add_u32_e32 v243, 0x4400000, v249
	global_store_dwordx4 v243, v[222:225], s[38:39]
	global_store_dwordx4 v243, v[228:231], s[38:39] offset:256

; __device__ __forceinline__ unsigned pk2(float lo, float hi) { unsigned r; asm("v_cvt_pk_bf16_f32 %0, %1, %2" : "=v"(r) : "v"(lo), "v"(hi)); return r; }
;     __device__ __forceinline__ void operator()(const f32x4 (&acc)[2][2][4][2], const Unit& u, int wr, int wc, int fr_, int fq_) const {
;     ...
;                 for (int bj = 0; bj < 2; ++bj) { f32x4 x[2];
;                     if (Xin) { x[0] = *(const f32x4*)(Xin + eo + bj * HALF); x[1] = *(const f32x4*)(Xin + eo + bj * HALF + 4); }
;                     else { const u32x4 xw = *(const u32x4*)(Xb + eo + bj * HALF); x[0] = (f32x4){bf_lo(xw.x), bf_hi(xw.x), bf_lo(xw.y), bf_hi(xw.y)}; x[1] = (f32x4){bf_lo(xw.z), bf_hi(xw.z), bf_lo(xw.w), bf_hi(xw.w)}; }
; #pragma unroll
;                     for (int n = 0; n < 2; ++n) { x[n] = x[n] + gt[bj][n] * acc[ai][bj][m][n];
;                         s += (x[n][0] * x[n][0] + x[n][1] * x[n][1]) + (x[n][2] * x[n][2] + x[n][3] * x[n][3]); }
;                     if (live) { u32x4 xo; xo.x = pk2(x[0][0], x[0][1]); xo.y = pk2(x[0][2], x[0][3]); xo.z = pk2(x[1][0], x[1][1]); xo.w = pk2(x[1][2], x[1][3]); *(u32x4*)(X + eo + bj * HALF) = xo; }
;                     if (gnext && live) { const f32x4 a = x[0] * gn[bj][0], b = x[1] * gn[bj][1];
;                         u32x4 w; w.x = pk2(a[0], a[1]); w.y = pk2(a[2], a[3]); w.z = pk2(b[0], b[1]); w.w = pk2(b[2], b[3]);
;                         *(u32x4*)(AN + (size_t)row * D + colb + bj * HALF) = w; } }
.Lp3_bf16:
	v_lshlrev_b32_e32 v242, 1, v249
	v_add_u32_e32 v242, 0x100000, v242
	v_lshlrev_b32_e32 v249, 1, v249
	v_add_u32_e32 v249, 0x100000, v249
	global_load_dwordx4 v[164:167], v242, s[38:39]
	global_load_dwordx4 v[168:171], v242, s[38:39] offset:256
	v_add_u32_e32 v242, 0x10000, v242
	global_load_dwordx4 v[184:187], v242, s[38:39]
	global_load_dwordx4 v[202:205], v242, s[38:39] offset:256
	v_add_u32_e32 v242, 0x10000, v242
	s_waitcnt vmcnt(3)
	v_and_b32_e32 v207, 0xffff0000, v164
	v_lshlrev_b32_e32 v206, 16, v164
	v_and_b32_e32 v209, 0xffff0000, v165
	v_lshlrev_b32_e32 v208, 16, v165
	v_and_b32_e32 v211, 0xffff0000, v166
	v_lshlrev_b32_e32 v210, 16, v166
	v_and_b32_e32 v213, 0xffff0000, v167
	v_lshlrev_b32_e32 v212, 16, v167
	s_waitcnt vmcnt(2)
	v_and_b32_e32 v215, 0xffff0000, v168
	v_lshlrev_b32_e32 v214, 16, v168
	v_and_b32_e32 v217, 0xffff0000, v169
	v_lshlrev_b32_e32 v216, 16, v169
	v_and_b32_e32 v219, 0xffff0000, v170
	v_lshlrev_b32_e32 v218, 16, v170
	v_and_b32_e32 v221, 0xffff0000, v171
	v_lshlrev_b32_e32 v220, 16, v171
	global_load_dwordx4 v[164:167], v242, s[38:39]
	global_load_dwordx4 v[168:171], v242, s[38:39] offset:256
	v_add_u32_e32 v242, 0x10000, v242
	v_pk_fma_f32 v[206:207], v[42:43], v[158:159], v[206:207]
	v_pk_fma_f32 v[208:209], v[44:45], v[160:161], v[208:209]
	v_pk_fma_f32 v[210:211], v[46:47], v[154:155], v[210:211]
	v_pk_fma_f32 v[212:213], v[48:49], v[156:157], v[212:213]
	v_pk_fma_f32 v[214:215], v[50:51], v[150:151], v[214:215]
	v_pk_fma_f32 v[216:217], v[52:53], v[152:153], v[216:217]
	v_pk_fma_f32 v[218:219], v[54:55], v[146:147], v[218:219]
	v_pk_fma_f32 v[220:221], v[56:57], v[148:149], v[220:221]
	v_pk_mul_f32 v[172:173], v[206:207], v[206:207]
	v_pk_fma_f32 v[172:173], v[208:209], v[208:209], v[172:173]
	v_pk_fma_f32 v[172:173], v[210:211], v[210:211], v[172:173]
	v_pk_fma_f32 v[172:173], v[212:213], v[212:213], v[172:173]
	v_pk_fma_f32 v[172:173], v[214:215], v[214:215], v[172:173]
	v_pk_fma_f32 v[172:173], v[216:217], v[216:217], v[172:173]
	v_pk_fma_f32 v[172:173], v[218:219], v[218:219], v[172:173]
	v_pk_fma_f32 v[172:173], v[220:221], v[220:221], v[172:173]
	v_add_f32_e32 v190, v172, v173
	v_cvt_pk_bf16_f32 v222, v206, v207
	v_cvt_pk_bf16_f32 v223, v208, v209
	v_cvt_pk_bf16_f32 v224, v210, v211
	v_cvt_pk_bf16_f32 v225, v212, v213
	global_store_dwordx4 v249, v[222:225], s[38:39]
	v_cvt_pk_bf16_f32 v228, v214, v215
	v_cvt_pk_bf16_f32 v229, v216, v217
	v_cvt_pk_bf16_f32 v230, v218, v219
	v_cvt_pk_bf16_f32 v231, v220, v221
	global_store_dwordx4 v249, v[228:231], s[38:39] offset:256
	s_cmp_eq_u32 s22, 0
	s_cbranch_scc1 .Lp3_noan_0_0
	v_pk_mul_f32 v[206:207], v[206:207], v[62:63]
	v_pk_mul_f32 v[208:209], v[208:209], v[64:65]
	v_pk_mul_f32 v[210:211], v[210:211], v[70:71]
	v_pk_mul_f32 v[212:213], v[212:213], v[72:73]
	v_cvt_pk_bf16_f32 v222, v206, v207
	v_cvt_pk_bf16_f32 v223, v208, v209
	v_cvt_pk_bf16_f32 v224, v210, v211
	v_cvt_pk_bf16_f32 v225, v212, v213
	v_pk_mul_f32 v[214:215], v[214:215], v[74:75]
	v_pk_mul_f32 v[216:217], v[216:217], v[76:77]
	v_pk_mul_f32 v[218:219], v[218:219], v[78:79]
	v_pk_mul_f32 v[220:221], v[220:221], v[80:81]
	v_cvt_pk_bf16_f32 v228, v214, v215
	v_cvt_pk_bf16_f32 v229, v216, v217
	v_cvt_pk_bf16_f32 v230, v218, v219
	v_cvt_pk_bf16_f32 v231, v220, v221
	v_add_u32_e32 v243, 0x4400000, v249
	global_store_dwordx4 v243, v[222:225], s[38:39]
	global_store_dwordx4 v243, v[228:231], s[38:39] offset:256
.Lp3_noan_0_0:
	v_add_u32_e32 v249, 0x10000, v249
	s_waitcnt vmcnt(5)
	v_and_b32_e32 v207, 0xffff0000, v184
	v_lshlrev_b32_e32 v206, 16, v184
	v_and_b32_e32 v209, 0xffff0000, v185
	v_lshlrev_b32_e32 v208, 16, v185
	v_and_b32_e32 v211, 0xffff0000, v186
	v_lshlrev_b32_e32 v210, 16, v186
	v_and_b32_e32 v213, 0xffff0000, v187
	v_lshlrev_b32_e32 v212, 16, v187
	s_waitcnt vmcnt(4)
	v_and_b32_e32 v215, 0xffff0000, v202
	v_lshlrev_b32_e32 v214, 16, v202
	v_and_b32_e32 v217, 0xffff0000, v203
	v_lshlrev_b32_e32 v216, 16, v203
	v_and_b32_e32 v219, 0xffff0000, v204
	v_lshlrev_b32_e32 v218, 16, v204
	v_and_b32_e32 v221, 0xffff0000, v205
	v_lshlrev_b32_e32 v220, 16, v205
	global_load_dwordx4 v[184:187], v242, s[38:39]
	global_load_dwordx4 v[202:205], v242, s[38:39] offset:256
	v_add_u32_e32 v242, 0x50000, v242
	v_pk_fma_f32 v[206:207], v[42:43], v[142:143], v[206:207]
	v_pk_fma_f32 v[208:209], v[44:45], v[144:145], v[208:209]
	v_pk_fma_f32 v[210:211], v[46:47], v[138:139], v[210:211]
	v_pk_fma_f32 v[212:213], v[48:49], v[140:141], v[212:213]
	v_pk_fma_f32 v[214:215], v[50:51], v[134:135], v[214:215]
	v_pk_fma_f32 v[216:217], v[52:53], v[136:137], v[216:217]
	v_pk_fma_f32 v[218:219], v[54:55], v[130:131], v[218:219]
	v_pk_fma_f32 v[220:221], v[56:57], v[132:133], v[220:221]
	v_pk_mul_f32 v[172:173], v[206:207], v[206:207]
	v_pk_fma_f32 v[172:173], v[208:209], v[208:209], v[172:173]
	v_pk_fma_f32 v[172:173], v[210:211], v[210:211], v[172:173]
	v_pk_fma_f32 v[172:173], v[212:213], v[212:213], v[172:173]
	v_pk_fma_f32 v[172:173], v[214:215], v[214:215], v[172:173]
	v_pk_fma_f32 v[172:173], v[216:217], v[216:217], v[172:173]
	v_pk_fma_f32 v[172:173], v[218:219], v[218:219], v[172:173]
	v_pk_fma_f32 v[172:173], v[220:221], v[220:221], v[172:173]
	v_add_f32_e32 v192, v172, v173
	v_cvt_pk_bf16_f32 v222, v206, v207
	v_cvt_pk_bf16_f32 v223, v208, v209
	v_cvt_pk_bf16_f32 v224, v210, v211
	v_cvt_pk_bf16_f32 v225, v212, v213
	global_store_dwordx4 v249, v[222:225], s[38:39]
	v_cvt_pk_bf16_f32 v228, v214, v215
	v_cvt_pk_bf16_f32 v229, v216, v217
	v_cvt_pk_bf16_f32 v230, v218, v219
	v_cvt_pk_bf16_f32 v231, v220, v221
	global_store_dwordx4 v249, v[228:231], s[38:39] offset:256
	s_cmp_eq_u32 s22, 0
	s_cbranch_scc1 .Lp3_noan_0_1
	v_pk_mul_f32 v[206:207], v[206:207], v[62:63]
	v_pk_mul_f32 v[208:209], v[208:209], v[64:65]
	v_pk_mul_f32 v[210:211], v[210:211], v[70:71]
	v_pk_mul_f32 v[212:213], v[212:213], v[72:73]
	v_cvt_pk_bf16_f32 v222, v206, v207
	v_cvt_pk_bf16_f32 v223, v208, v209
	v_cvt_pk_bf16_f32 v224, v210, v211
	v_cvt_pk_bf16_f32 v225, v212, v213
	v_pk_mul_f32 v[214:215], v[214:215], v[74:75]
	v_pk_mul_f32 v[216:217], v[216:217], v[76:77]
	v_pk_mul_f32 v[218:219], v[218:219], v[78:79]
	v_pk_mul_f32 v[220:221], v[220:221], v[80:81]
	v_cvt_pk_bf16_f32 v228, v214, v215
	v_cvt_pk_bf16_f32 v229, v216, v217
	v_cvt_pk_bf16_f32 v230, v218, v219
	v_cvt_pk_bf16_f32 v231, v220, v221
	v_add_u32_e32 v243, 0x4400000, v249
	global_store_dwordx4 v243, v[222:225], s[38:39]
	global_store_dwordx4 v243, v[228:231], s[38:39] offset:256
; __device__ __forceinline__ unsigned pk2(float lo, float hi) { unsigned r; asm("v_cvt_pk_bf16_f32 %0, %1, %2" : "=v"(r) : "v"(lo), "v"(hi)); return r; }
;     __device__ __forceinline__ void operator()(const f32x4 (&acc)[2][2][4][2], const Unit& u, int wr, int wc, int fr_, int fq_) const {
;     ...
;                 for (int bj = 0; bj < 2; ++bj) { f32x4 x[2];
;                     if (Xin) { x[0] = *(const f32x4*)(Xin + eo + bj * HALF); x[1] = *(const f32x4*)(Xin + eo + bj * HALF + 4); }
;                     else { const u32x4 xw = *(const u32x4*)(Xb + eo + bj * HALF); x[0] = (f32x4){bf_lo(xw.x), bf_hi(xw.x), bf_lo(xw.y), bf_hi(xw.y)}; x[1] = (f32x4){bf_lo(xw.z), bf_hi(xw.z), bf_lo(xw.w), bf_hi(xw.w)}; }
; #pragma unroll
;                     for (int n = 0; n < 2; ++n) { x[n] = x[n] + gt[bj][n] * acc[ai][bj][m][n];
;                         s += (x[n][0] * x[n][0] + x[n][1] * x[n][1]) + (x[n][2] * x[n][2] + x[n][3] * x[n][3]); }
;                     if (live) { u32x4 xo; xo.x = pk2(x[0][0], x[0][1]); xo.y = pk2(x[0][2], x[0][3]); xo.z = pk2(x[1][0], x[1][1]); xo.w = pk2(x[1][2], x[1][3]); *(u32x4*)(X + eo + bj * HALF) = xo; }
;                     if (gnext && live) { const f32x4 a = x[0] * gn[bj][0], b = x[1] * gn[bj][1];
;                         u32x4 w; w.x = pk2(a[0], a[1]); w.y = pk2(a[2], a[3]); w.z = pk2(b[0], b[1]); w.w = pk2(b[2], b[3]);
;                         *(u32x4*)(AN + (size_t)row * D + colb + bj * HALF) = w; } }
.Lp3_noan_0_1:
	v_add_u32_e32 v249, 0x10000, v249
	s_waitcnt vmcnt(7)
	v_and_b32_e32 v207, 0xffff0000, v164
	v_lshlrev_b32_e32 v206, 16, v164
	v_and_b32_e32 v209, 0xffff0000, v165
	v_lshlrev_b32_e32 v208, 16, v165
	v_and_b32_e32 v211, 0xffff0000, v166
	v_lshlrev_b32_e32 v210, 16, v166
	v_and_b32_e32 v213, 0xffff0000, v167
	v_lshlrev_b32_e32 v212, 16, v167
	s_waitcnt vmcnt(6)
	v_and_b32_e32 v215, 0xffff0000, v168
	v_lshlrev_b32_e32 v214, 16, v168
	v_and_b32_e32 v217, 0xffff0000, v169
	v_lshlrev_b32_e32 v216, 16, v169
	v_and_b32_e32 v219, 0xffff0000, v170
	v_lshlrev_b32_e32 v218, 16, v170
	v_and_b32_e32 v221, 0xffff0000, v171
	v_lshlrev_b32_e32 v220, 16, v171
	global_load_dwordx4 v[164:167], v242, s[38:39]
	global_load_dwordx4 v[168:171], v242, s[38:39] offset:256
	v_add_u32_e32 v242, 0x10000, v242
	v_pk_fma_f32 v[206:207], v[42:43], v[126:127], v[206:207]
	v_pk_fma_f32 v[208:209], v[44:45], v[128:129], v[208:209]
	v_pk_fma_f32 v[210:211], v[46:47], v[122:123], v[210:211]
	v_pk_fma_f32 v[212:213], v[48:49], v[124:125], v[212:213]
	v_pk_fma_f32 v[214:215], v[50:51], v[118:119], v[214:215]
	v_pk_fma_f32 v[216:217], v[52:53], v[120:121], v[216:217]
	v_pk_fma_f32 v[218:219], v[54:55], v[114:115], v[218:219]
	v_pk_fma_f32 v[220:221], v[56:57], v[116:117], v[220:221]
	v_pk_mul_f32 v[172:173], v[206:207], v[206:207]
	v_pk_fma_f32 v[172:173], v[208:209], v[208:209], v[172:173]
	v_pk_fma_f32 v[172:173], v[210:211], v[210:211], v[172:173]
	v_pk_fma_f32 v[172:173], v[212:213], v[212:213], v[172:173]
	v_pk_fma_f32 v[172:173], v[214:215], v[214:215], v[172:173]
	v_pk_fma_f32 v[172:173], v[216:217], v[216:217], v[172:173]
	v_pk_fma_f32 v[172:173], v[218:219], v[218:219], v[172:173]
	v_pk_fma_f32 v[172:173], v[220:221], v[220:221], v[172:173]
	v_add_f32_e32 v226, v172, v173
	v_cvt_pk_bf16_f32 v222, v206, v207
	v_cvt_pk_bf16_f32 v223, v208, v209
	v_cvt_pk_bf16_f32 v224, v210, v211
	v_cvt_pk_bf16_f32 v225, v212, v213
	global_store_dwordx4 v249, v[222:225], s[38:39]
	v_cvt_pk_bf16_f32 v228, v214, v215
	v_cvt_pk_bf16_f32 v229, v216, v217
	v_cvt_pk_bf16_f32 v230, v218, v219
	v_cvt_pk_bf16_f32 v231, v220, v221
	global_store_dwordx4 v249, v[228:231], s[38:39] offset:256
	s_cmp_eq_u32 s22, 0
	s_cbranch_scc1 .Lp3_noan_0_2
	v_pk_mul_f32 v[206:207], v[206:207], v[62:63]
	v_pk_mul_f32 v[208:209], v[208:209], v[64:65]
	v_pk_mul_f32 v[210:211], v[210:211], v[70:71]
	v_pk_mul_f32 v[212:213], v[212:213], v[72:73]
	v_cvt_pk_bf16_f32 v222, v206, v207
	v_cvt_pk_bf16_f32 v223, v208, v209
	v_cvt_pk_bf16_f32 v224, v210, v211
	v_cvt_pk_bf16_f32 v225, v212, v213
	v_pk_mul_f32 v[214:215], v[214:215], v[74:75]
	v_pk_mul_f32 v[216:217], v[216:217], v[76:77]
	v_pk_mul_f32 v[218:219], v[218:219], v[78:79]
	v_pk_mul_f32 v[220:221], v[220:221], v[80:81]
	v_cvt_pk_bf16_f32 v228, v214, v215
	v_cvt_pk_bf16_f32 v229, v216, v217
	v_cvt_pk_bf16_f32 v230, v218, v219
	v_cvt_pk_bf16_f32 v231, v220, v221
	v_add_u32_e32 v243, 0x4400000, v249
	global_store_dwordx4 v243, v[222:225], s[38:39]
	global_store_dwordx4 v243, v[228:231], s[38:39] offset:256
.Lp3_noan_0_2:
	v_add_u32_e32 v249, 0x10000, v249
	s_waitcnt vmcnt(7)
	v_and_b32_e32 v207, 0xffff0000, v184
	v_lshlrev_b32_e32 v206, 16, v184
	v_and_b32_e32 v209, 0xffff0000, v185
	v_lshlrev_b32_e32 v208, 16, v185
	v_and_b32_e32 v211, 0xffff0000, v186
	v_lshlrev_b32_e32 v210, 16, v186
	v_and_b32_e32 v213, 0xffff0000, v187
	v_lshlrev_b32_e32 v212, 16, v187
	s_waitcnt vmcnt(6)
	v_and_b32_e32 v215, 0xffff0000, v202
	v_lshlrev_b32_e32 v214, 16, v202
	v_and_b32_e32 v217, 0xffff0000, v203
	v_lshlrev_b32_e32 v216, 16, v203
	v_and_b32_e32 v219, 0xffff0000, v204
	v_lshlrev_b32_e32 v218, 16, v204
	v_and_b32_e32 v221, 0xffff0000, v205
	v_lshlrev_b32_e32 v220, 16, v205
	global_load_dwordx4 v[184:187], v242, s[38:39]
	global_load_dwordx4 v[202:205], v242, s[38:39] offset:256
	v_add_u32_e32 v242, 0x10000, v242
	v_pk_fma_f32 v[206:207], v[42:43], v[110:111], v[206:207]
	v_pk_fma_f32 v[208:209], v[44:45], v[112:113], v[208:209]
	v_pk_fma_f32 v[210:211], v[46:47], v[106:107], v[210:211]
	v_pk_fma_f32 v[212:213], v[48:49], v[108:109], v[212:213]
	v_pk_fma_f32 v[214:215], v[50:51], v[102:103], v[214:215]
	v_pk_fma_f32 v[216:217], v[52:53], v[104:105], v[216:217]
	v_pk_fma_f32 v[218:219], v[54:55], v[98:99], v[218:219]
	v_pk_fma_f32 v[220:221], v[56:57], v[100:101], v[220:221]
	v_pk_mul_f32 v[172:173], v[206:207], v[206:207]
	v_pk_fma_f32 v[172:173], v[208:209], v[208:209], v[172:173]
	v_pk_fma_f32 v[172:173], v[210:211], v[210:211], v[172:173]
	v_pk_fma_f32 v[172:173], v[212:213], v[212:213], v[172:173]
	v_pk_fma_f32 v[172:173], v[214:215], v[214:215], v[172:173]
	v_pk_fma_f32 v[172:173], v[216:217], v[216:217], v[172:173]
	v_pk_fma_f32 v[172:173], v[218:219], v[218:219], v[172:173]
	v_pk_fma_f32 v[172:173], v[220:221], v[220:221], v[172:173]
	v_add_f32_e32 v236, v172, v173
	v_cvt_pk_bf16_f32 v222, v206, v207
	v_cvt_pk_bf16_f32 v223, v208, v209
	v_cvt_pk_bf16_f32 v224, v210, v211
	v_cvt_pk_bf16_f32 v225, v212, v213
	global_store_dwordx4 v249, v[222:225], s[38:39]
	v_cvt_pk_bf16_f32 v228, v214, v215
	v_cvt_pk_bf16_f32 v229, v216, v217
	v_cvt_pk_bf16_f32 v230, v218, v219
	v_cvt_pk_bf16_f32 v231, v220, v221
	global_store_dwordx4 v249, v[228:231], s[38:39] offset:256
	s_cmp_eq_u32 s22, 0
	s_cbranch_scc1 .Lp3_noan_0_3
	v_pk_mul_f32 v[206:207], v[206:207], v[62:63]
	v_pk_mul_f32 v[208:209], v[208:209], v[64:65]
	v_pk_mul_f32 v[210:211], v[210:211], v[70:71]
	v_pk_mul_f32 v[212:213], v[212:213], v[72:73]
	v_cvt_pk_bf16_f32 v222, v206, v207
	v_cvt_pk_bf16_f32 v223, v208, v209
	v_cvt_pk_bf16_f32 v224, v210, v211
	v_cvt_pk_bf16_f32 v225, v212, v213
	v_pk_mul_f32 v[214:215], v[214:215], v[74:75]
	v_pk_mul_f32 v[216:217], v[216:217], v[76:77]
	v_pk_mul_f32 v[218:219], v[218:219], v[78:79]
	v_pk_mul_f32 v[220:221], v[220:221], v[80:81]
	v_cvt_pk_bf16_f32 v228, v214, v215
	v_cvt_pk_bf16_f32 v229, v216, v217
	v_cvt_pk_bf16_f32 v230, v218, v219
	v_cvt_pk_bf16_f32 v231, v220, v221
	v_add_u32_e32 v243, 0x4400000, v249
	global_store_dwordx4 v243, v[222:225], s[38:39]
	global_store_dwordx4 v243, v[228:231], s[38:39] offset:256
; __device__ __forceinline__ unsigned pk2(float lo, float hi) { unsigned r; asm("v_cvt_pk_bf16_f32 %0, %1, %2" : "=v"(r) : "v"(lo), "v"(hi)); return r; }
;     __device__ __forceinline__ void operator()(const f32x4 (&acc)[2][2][4][2], const Unit& u, int wr, int wc, int fr_, int fq_) const {
;     ...
;                 for (int bj = 0; bj < 2; ++bj) { f32x4 x[2];
;                     if (Xin) { x[0] = *(const f32x4*)(Xin + eo + bj * HALF); x[1] = *(const f32x4*)(Xin + eo + bj * HALF + 4); }
;                     else { const u32x4 xw = *(const u32x4*)(Xb + eo + bj * HALF); x[0] = (f32x4){bf_lo(xw.x), bf_hi(xw.x), bf_lo(xw.y), bf_hi(xw.y)}; x[1] = (f32x4){bf_lo(xw.z), bf_hi(xw.z), bf_lo(xw.w), bf_hi(xw.w)}; }
; #pragma unroll
;                     for (int n = 0; n < 2; ++n) { x[n] = x[n] + gt[bj][n] * acc[ai][bj][m][n];
;                         s += (x[n][0] * x[n][0] + x[n][1] * x[n][1]) + (x[n][2] * x[n][2] + x[n][3] * x[n][3]); }
;                     if (live) { u32x4 xo; xo.x = pk2(x[0][0], x[0][1]); xo.y = pk2(x[0][2], x[0][3]); xo.z = pk2(x[1][0], x[1][1]); xo.w = pk2(x[1][2], x[1][3]); *(u32x4*)(X + eo + bj * HALF) = xo; }
;                     if (gnext && live) { const f32x4 a = x[0] * gn[bj][0], b = x[1] * gn[bj][1];
;                         u32x4 w; w.x = pk2(a[0], a[1]); w.y = pk2(a[2], a[3]); w.z = pk2(b[0], b[1]); w.w = pk2(b[2], b[3]);
;                         *(u32x4*)(AN + (size_t)row * D + colb + bj * HALF) = w; } }
.Lp3_noan_0_3:
	v_add_u32_e32 v249, 0x50000, v249
	s_waitcnt vmcnt(7)
	v_and_b32_e32 v207, 0xffff0000, v164
	v_lshlrev_b32_e32 v206, 16, v164
	v_and_b32_e32 v209, 0xffff0000, v165
	v_lshlrev_b32_e32 v208, 16, v165
	v_and_b32_e32 v211, 0xffff0000, v166
	v_lshlrev_b32_e32 v210, 16, v166
	v_and_b32_e32 v213, 0xffff0000, v167
	v_lshlrev_b32_e32 v212, 16, v167
	s_waitcnt vmcnt(6)
	v_and_b32_e32 v215, 0xffff0000, v168
	v_lshlrev_b32_e32 v214, 16, v168
	v_and_b32_e32 v217, 0xffff0000, v169
	v_lshlrev_b32_e32 v216, 16, v169
	v_and_b32_e32 v219, 0xffff0000, v170
	v_lshlrev_b32_e32 v218, 16, v170
	v_and_b32_e32 v221, 0xffff0000, v171
	v_lshlrev_b32_e32 v220, 16, v171
	global_load_dwordx4 v[164:167], v242, s[38:39]
	global_load_dwordx4 v[168:171], v242, s[38:39] offset:256
	v_add_u32_e32 v242, 0x10000, v242
	v_pk_fma_f32 v[206:207], v[42:43], v[94:95], v[206:207]
	v_pk_fma_f32 v[208:209], v[44:45], v[96:97], v[208:209]
	v_pk_fma_f32 v[210:211], v[46:47], v[90:91], v[210:211]
	v_pk_fma_f32 v[212:213], v[48:49], v[92:93], v[212:213]
	v_pk_fma_f32 v[214:215], v[50:51], v[86:87], v[214:215]
	v_pk_fma_f32 v[216:217], v[52:53], v[88:89], v[216:217]
	v_pk_fma_f32 v[218:219], v[54:55], v[82:83], v[218:219]
	v_pk_fma_f32 v[220:221], v[56:57], v[84:85], v[220:221]
	v_pk_mul_f32 v[172:173], v[206:207], v[206:207]
	v_pk_fma_f32 v[172:173], v[208:209], v[208:209], v[172:173]
	v_pk_fma_f32 v[172:173], v[210:211], v[210:211], v[172:173]
	v_pk_fma_f32 v[172:173], v[212:213], v[212:213], v[172:173]
	v_pk_fma_f32 v[172:173], v[214:215], v[214:215], v[172:173]
	v_pk_fma_f32 v[172:173], v[216:217], v[216:217], v[172:173]
	v_pk_fma_f32 v[172:173], v[218:219], v[218:219], v[172:173]
	v_pk_fma_f32 v[172:173], v[220:221], v[220:221], v[172:173]
	v_add_f32_e32 v239, v172, v173
	v_cvt_pk_bf16_f32 v222, v206, v207
	v_cvt_pk_bf16_f32 v223, v208, v209
	v_cvt_pk_bf16_f32 v224, v210, v211
	v_cvt_pk_bf16_f32 v225, v212, v213
	global_store_dwordx4 v249, v[222:225], s[38:39]
	v_cvt_pk_bf16_f32 v228, v214, v215
	v_cvt_pk_bf16_f32 v229, v216, v217
	v_cvt_pk_bf16_f32 v230, v218, v219
	v_cvt_pk_bf16_f32 v231, v220, v221
	global_store_dwordx4 v249, v[228:231], s[38:39] offset:256
	s_cmp_eq_u32 s22, 0
	s_cbranch_scc1 .Lp3_noan_0_4
	v_pk_mul_f32 v[206:207], v[206:207], v[62:63]
	v_pk_mul_f32 v[208:209], v[208:209], v[64:65]
	v_pk_mul_f32 v[210:211], v[210:211], v[70:71]
	v_pk_mul_f32 v[212:213], v[212:213], v[72:73]
	v_cvt_pk_bf16_f32 v222, v206, v207
	v_cvt_pk_bf16_f32 v223, v208, v209
	v_cvt_pk_bf16_f32 v224, v210, v211
	v_cvt_pk_bf16_f32 v225, v212, v213
	v_pk_mul_f32 v[214:215], v[214:215], v[74:75]
	v_pk_mul_f32 v[216:217], v[216:217], v[76:77]
	v_pk_mul_f32 v[218:219], v[218:219], v[78:79]
	v_pk_mul_f32 v[220:221], v[220:221], v[80:81]
	v_cvt_pk_bf16_f32 v228, v214, v215
	v_cvt_pk_bf16_f32 v229, v216, v217
	v_cvt_pk_bf16_f32 v230, v218, v219
	v_cvt_pk_bf16_f32 v231, v220, v221
	v_add_u32_e32 v243, 0x4400000, v249
	global_store_dwordx4 v243, v[222:225], s[38:39]
	global_store_dwordx4 v243, v[228:231], s[38:39] offset:256
.Lp3_noan_0_4:
	v_add_u32_e32 v249, 0x10000, v249
	s_waitcnt vmcnt(7)
	v_and_b32_e32 v207, 0xffff0000, v184
	v_lshlrev_b32_e32 v206, 16, v184
	v_and_b32_e32 v209, 0xffff0000, v185
	v_lshlrev_b32_e32 v208, 16, v185
	v_and_b32_e32 v211, 0xffff0000, v186
	v_lshlrev_b32_e32 v210, 16, v186
	v_and_b32_e32 v213, 0xffff0000, v187
	v_lshlrev_b32_e32 v212, 16, v187
	s_waitcnt vmcnt(6)
	v_and_b32_e32 v215, 0xffff0000, v202
	v_lshlrev_b32_e32 v214, 16, v202
	v_and_b32_e32 v217, 0xffff0000, v203
	v_lshlrev_b32_e32 v216, 16, v203
	v_and_b32_e32 v219, 0xffff0000, v204
	v_lshlrev_b32_e32 v218, 16, v204
	v_and_b32_e32 v221, 0xffff0000, v205
	v_lshlrev_b32_e32 v220, 16, v205
	global_load_dwordx4 v[184:187], v242, s[38:39]
	global_load_dwordx4 v[202:205], v242, s[38:39] offset:256
	v_pk_fma_f32 v[206:207], v[42:43], v[66:67], v[206:207]
	v_pk_fma_f32 v[208:209], v[44:45], v[68:69], v[208:209]
	v_pk_fma_f32 v[210:211], v[46:47], v[58:59], v[210:211]
	v_pk_fma_f32 v[212:213], v[48:49], v[60:61], v[212:213]
	v_pk_fma_f32 v[214:215], v[50:51], v[38:39], v[214:215]
	v_pk_fma_f32 v[216:217], v[52:53], v[40:41], v[216:217]
	v_pk_fma_f32 v[218:219], v[54:55], v[34:35], v[218:219]
	v_pk_fma_f32 v[220:221], v[56:57], v[36:37], v[220:221]
	v_pk_mul_f32 v[172:173], v[206:207], v[206:207]
	v_pk_fma_f32 v[172:173], v[208:209], v[208:209], v[172:173]
	v_pk_fma_f32 v[172:173], v[210:211], v[210:211], v[172:173]
	v_pk_fma_f32 v[172:173], v[212:213], v[212:213], v[172:173]
	v_pk_fma_f32 v[172:173], v[214:215], v[214:215], v[172:173]
	v_pk_fma_f32 v[172:173], v[216:217], v[216:217], v[172:173]
	v_pk_fma_f32 v[172:173], v[218:219], v[218:219], v[172:173]
	v_pk_fma_f32 v[172:173], v[220:221], v[220:221], v[172:173]
	v_add_f32_e32 v252, v172, v173
	v_cvt_pk_bf16_f32 v222, v206, v207
	v_cvt_pk_bf16_f32 v223, v208, v209
	v_cvt_pk_bf16_f32 v224, v210, v211
	v_cvt_pk_bf16_f32 v225, v212, v213
	global_store_dwordx4 v249, v[222:225], s[38:39]
	v_cvt_pk_bf16_f32 v228, v214, v215
	v_cvt_pk_bf16_f32 v229, v216, v217
	v_cvt_pk_bf16_f32 v230, v218, v219
	v_cvt_pk_bf16_f32 v231, v220, v221
	global_store_dwordx4 v249, v[228:231], s[38:39] offset:256
	s_cmp_eq_u32 s22, 0
	s_cbranch_scc1 .Lp3_noan_0_5
	v_pk_mul_f32 v[206:207], v[206:207], v[62:63]
	v_pk_mul_f32 v[208:209], v[208:209], v[64:65]
	v_pk_mul_f32 v[210:211], v[210:211], v[70:71]
	v_pk_mul_f32 v[212:213], v[212:213], v[72:73]
	v_cvt_pk_bf16_f32 v222, v206, v207
	v_cvt_pk_bf16_f32 v223, v208, v209
	v_cvt_pk_bf16_f32 v224, v210, v211
	v_cvt_pk_bf16_f32 v225, v212, v213
	v_pk_mul_f32 v[214:215], v[214:215], v[74:75]
	v_pk_mul_f32 v[216:217], v[216:217], v[76:77]
	v_pk_mul_f32 v[218:219], v[218:219], v[78:79]
	v_pk_mul_f32 v[220:221], v[220:221], v[80:81]
	v_cvt_pk_bf16_f32 v228, v214, v215
	v_cvt_pk_bf16_f32 v229, v216, v217
	v_cvt_pk_bf16_f32 v230, v218, v219
	v_cvt_pk_bf16_f32 v231, v220, v221
	v_add_u32_e32 v243, 0x4400000, v249
	global_store_dwordx4 v243, v[222:225], s[38:39]
	global_store_dwordx4 v243, v[228:231], s[38:39] offset:256
; __device__ __forceinline__ unsigned pk2(float lo, float hi) { unsigned r; asm("v_cvt_pk_bf16_f32 %0, %1, %2" : "=v"(r) : "v"(lo), "v"(hi)); return r; }
;     __device__ __forceinline__ void operator()(const f32x4 (&acc)[2][2][4][2], const Unit& u, int wr, int wc, int fr_, int fq_) const {
;     ...
;                 for (int bj = 0; bj < 2; ++bj) { f32x4 x[2];
;                     if (Xin) { x[0] = *(const f32x4*)(Xin + eo + bj * HALF); x[1] = *(const f32x4*)(Xin + eo + bj * HALF + 4); }
;                     else { const u32x4 xw = *(const u32x4*)(Xb + eo + bj * HALF); x[0] = (f32x4){bf_lo(xw.x), bf_hi(xw.x), bf_lo(xw.y), bf_hi(xw.y)}; x[1] = (f32x4){bf_lo(xw.z), bf_hi(xw.z), bf_lo(xw.w), bf_hi(xw.w)}; }
; #pragma unroll
;                     for (int n = 0; n < 2; ++n) { x[n] = x[n] + gt[bj][n] * acc[ai][bj][m][n];
;                         s += (x[n][0] * x[n][0] + x[n][1] * x[n][1]) + (x[n][2] * x[n][2] + x[n][3] * x[n][3]); }
;                     if (live) { u32x4 xo; xo.x = pk2(x[0][0], x[0][1]); xo.y = pk2(x[0][2], x[0][3]); xo.z = pk2(x[1][0], x[1][1]); xo.w = pk2(x[1][2], x[1][3]); *(u32x4*)(X + eo + bj * HALF) = xo; }
;                     if (gnext && live) { const f32x4 a = x[0] * gn[bj][0], b = x[1] * gn[bj][1];
;                         u32x4 w; w.x = pk2(a[0], a[1]); w.y = pk2(a[2], a[3]); w.z = pk2(b[0], b[1]); w.w = pk2(b[2], b[3]);
;                         *(u32x4*)(AN + (size_t)row * D + colb + bj * HALF) = w; } }
.Lp3_noan_0_5:
	v_add_u32_e32 v249, 0x10000, v249
	s_waitcnt vmcnt(7)
	v_and_b32_e32 v207, 0xffff0000, v164
	v_lshlrev_b32_e32 v206, 16, v164
	v_and_b32_e32 v209, 0xffff0000, v165
	v_lshlrev_b32_e32 v208, 16, v165
	v_and_b32_e32 v211, 0xffff0000, v166
	v_lshlrev_b32_e32 v210, 16, v166
	v_and_b32_e32 v213, 0xffff0000, v167
	v_lshlrev_b32_e32 v212, 16, v167
	s_waitcnt vmcnt(6)
	v_and_b32_e32 v215, 0xffff0000, v168
	v_lshlrev_b32_e32 v214, 16, v168
	v_and_b32_e32 v217, 0xffff0000, v169
	v_lshlrev_b32_e32 v216, 16, v169
	v_and_b32_e32 v219, 0xffff0000, v170
	v_lshlrev_b32_e32 v218, 16, v170
	v_and_b32_e32 v221, 0xffff0000, v171
	v_lshlrev_b32_e32 v220, 16, v171
	v_pk_fma_f32 v[206:207], v[42:43], v[30:31], v[206:207]
	v_pk_fma_f32 v[208:209], v[44:45], v[32:33], v[208:209]
	v_pk_fma_f32 v[210:211], v[46:47], v[26:27], v[210:211]
	v_pk_fma_f32 v[212:213], v[48:49], v[28:29], v[212:213]
	v_pk_fma_f32 v[214:215], v[50:51], v[22:23], v[214:215]
	v_pk_fma_f32 v[216:217], v[52:53], v[24:25], v[216:217]
	v_pk_fma_f32 v[218:219], v[54:55], v[18:19], v[218:219]
	v_pk_fma_f32 v[220:221], v[56:57], v[20:21], v[220:221]
	v_pk_mul_f32 v[172:173], v[206:207], v[206:207]
	v_pk_fma_f32 v[172:173], v[208:209], v[208:209], v[172:173]
	v_pk_fma_f32 v[172:173], v[210:211], v[210:211], v[172:173]
	v_pk_fma_f32 v[172:173], v[212:213], v[212:213], v[172:173]
	v_pk_fma_f32 v[172:173], v[214:215], v[214:215], v[172:173]
	v_pk_fma_f32 v[172:173], v[216:217], v[216:217], v[172:173]
	v_pk_fma_f32 v[172:173], v[218:219], v[218:219], v[172:173]
	v_pk_fma_f32 v[172:173], v[220:221], v[220:221], v[172:173]
	v_add_f32_e32 v251, v172, v173
	v_cvt_pk_bf16_f32 v222, v206, v207
	v_cvt_pk_bf16_f32 v223, v208, v209
	v_cvt_pk_bf16_f32 v224, v210, v211
	v_cvt_pk_bf16_f32 v225, v212, v213
	global_store_dwordx4 v249, v[222:225], s[38:39]
	v_cvt_pk_bf16_f32 v228, v214, v215
	v_cvt_pk_bf16_f32 v229, v216, v217
	v_cvt_pk_bf16_f32 v230, v218, v219
	v_cvt_pk_bf16_f32 v231, v220, v221
	global_store_dwordx4 v249, v[228:231], s[38:39] offset:256
	s_cmp_eq_u32 s22, 0
	s_cbranch_scc1 .Lp3_noan_0_6
	v_pk_mul_f32 v[206:207], v[206:207], v[62:63]
	v_pk_mul_f32 v[208:209], v[208:209], v[64:65]
	v_pk_mul_f32 v[210:211], v[210:211], v[70:71]
	v_pk_mul_f32 v[212:213], v[212:213], v[72:73]
	v_cvt_pk_bf16_f32 v222, v206, v207
	v_cvt_pk_bf16_f32 v223, v208, v209
	v_cvt_pk_bf16_f32 v224, v210, v211
	v_cvt_pk_bf16_f32 v225, v212, v213
	v_pk_mul_f32 v[214:215], v[214:215], v[74:75]
	v_pk_mul_f32 v[216:217], v[216:217], v[76:77]
	v_pk_mul_f32 v[218:219], v[218:219], v[78:79]
	v_pk_mul_f32 v[220:221], v[220:221], v[80:81]
	v_cvt_pk_bf16_f32 v228, v214, v215
	v_cvt_pk_bf16_f32 v229, v216, v217
	v_cvt_pk_bf16_f32 v230, v218, v219
	v_cvt_pk_bf16_f32 v231, v220, v221
	v_add_u32_e32 v243, 0x4400000, v249
	global_store_dwordx4 v243, v[222:225], s[38:39]
	global_store_dwordx4 v243, v[228:231], s[38:39] offset:256
; #define PG8_BAR __builtin_amdgcn_s_barrier()
; template <class Epi, class Sched, bool ALIGN_EPI = false, bool SP2 = false>
; __device__ __forceinline__ void gemm_phase(PG8_LAS unsigned char* lds, const Gemm g, const Sched& S, const Epi& E, const int wave_s) {
;     ...
;         if constexpr (ALIGN_EPI) { if (wr == 0) PG8_BAR; }
;         if constexpr (!Epi::AFTER_DRAIN) { E(acc, cur, wr, wc, fr, fq); S.done(cur); }
;         if (!has_next) break;
; #pragma unroll
;         for (int a = 0; a < 2; ++a)
; #pragma unroll
;             for (int b = 0; b < 2; ++b)
; #pragma unroll
;                 for (int m = 0; m < 4; ++m)
; #pragma unroll
;                     for (int n = 0; n < 2; ++n) acc[a][b][m][n] = (f32x4){0.f, 0.f, 0.f, 0.f};
;         cur = nxt; cA = nA; cB = nB; ++ui;
;         if constexpr (ALIGN_EPI) { if (wr == 1) PG8_BAR; }
;     }
;     __device__ __forceinline__ void operator()(const f32x4 (&acc)[2][2][4][2], const Unit& u, int wr, int wc, int fr_, int fq_) const {
;     ...
;                 for (int bj = 0; bj < 2; ++bj) { f32x4 x[2];
;                     if (Xin) { x[0] = *(const f32x4*)(Xin + eo + bj * HALF); x[1] = *(const f32x4*)(Xin + eo + bj * HALF + 4); }
;                     else { const u32x4 xw = *(const u32x4*)(Xb + eo + bj * HALF); x[0] = (f32x4){bf_lo(xw.x), bf_hi(xw.x), bf_lo(xw.y), bf_hi(xw.y)}; x[1] = (f32x4){bf_lo(xw.z), bf_hi(xw.z), bf_lo(xw.w), bf_hi(xw.w)}; }
; #pragma unroll
;                     for (int n = 0; n < 2; ++n) { x[n] = x[n] + gt[bj][n] * acc[ai][bj][m][n];
;                         s += (x[n][0] * x[n][0] + x[n][1] * x[n][1]) + (x[n][2] * x[n][2] + x[n][3] * x[n][3]); }
;                     if (live) { u32x4 xo; xo.x = pk2(x[0][0], x[0][1]); xo.y = pk2(x[0][2], x[0][3]); xo.z = pk2(x[1][0], x[1][1]); xo.w = pk2(x[1][2], x[1][3]); *(u32x4*)(X + eo + bj * HALF) = xo; }
;                     if (gnext && live) { const f32x4 a = x[0] * gn[bj][0], b = x[1] * gn[bj][1];
;                         u32x4 w; w.x = pk2(a[0], a[1]); w.y = pk2(a[2], a[3]); w.z = pk2(b[0], b[1]); w.w = pk2(b[2], b[3]);
;                         *(u32x4*)(AN + (size_t)row * D + colb + bj * HALF) = w; } }
;                 s += __shfl_xor(s, 16); s += __shfl_xor(s, 32);
;                 if (fq == 0 && live) ssq[((size_t)u.pn * MT + row) * 4 + wc] = s; }
.Lp3_noan_0_6:
	v_add_u32_e32 v249, 0x10000, v249
	s_waitcnt vmcnt(5)
	v_and_b32_e32 v207, 0xffff0000, v184
	v_lshlrev_b32_e32 v206, 16, v184
	v_and_b32_e32 v209, 0xffff0000, v185
	v_lshlrev_b32_e32 v208, 16, v185
	v_and_b32_e32 v211, 0xffff0000, v186
	v_lshlrev_b32_e32 v210, 16, v186
	v_and_b32_e32 v213, 0xffff0000, v187
	v_lshlrev_b32_e32 v212, 16, v187
	s_waitcnt vmcnt(4)
	v_and_b32_e32 v215, 0xffff0000, v202
	v_lshlrev_b32_e32 v214, 16, v202
	v_and_b32_e32 v217, 0xffff0000, v203
	v_lshlrev_b32_e32 v216, 16, v203
	v_and_b32_e32 v219, 0xffff0000, v204
	v_lshlrev_b32_e32 v218, 16, v204
	v_and_b32_e32 v221, 0xffff0000, v205
	v_lshlrev_b32_e32 v220, 16, v205
	v_pk_fma_f32 v[206:207], v[42:43], v[14:15], v[206:207]
	v_pk_fma_f32 v[208:209], v[44:45], v[16:17], v[208:209]
	v_pk_fma_f32 v[210:211], v[46:47], v[10:11], v[210:211]
	v_pk_fma_f32 v[212:213], v[48:49], v[12:13], v[212:213]
	v_pk_fma_f32 v[214:215], v[50:51], v[6:7], v[214:215]
	v_pk_fma_f32 v[216:217], v[52:53], v[8:9], v[216:217]
	v_pk_fma_f32 v[218:219], v[54:55], v[2:3], v[218:219]
	v_pk_fma_f32 v[220:221], v[56:57], v[4:5], v[220:221]
	v_pk_mul_f32 v[172:173], v[206:207], v[206:207]
	v_pk_fma_f32 v[172:173], v[208:209], v[208:209], v[172:173]
	v_pk_fma_f32 v[172:173], v[210:211], v[210:211], v[172:173]
	v_pk_fma_f32 v[172:173], v[212:213], v[212:213], v[172:173]
	v_pk_fma_f32 v[172:173], v[214:215], v[214:215], v[172:173]
	v_pk_fma_f32 v[172:173], v[216:217], v[216:217], v[172:173]
	v_pk_fma_f32 v[172:173], v[218:219], v[218:219], v[172:173]
	v_pk_fma_f32 v[172:173], v[220:221], v[220:221], v[172:173]
	v_add_f32_e32 v250, v172, v173
	v_cvt_pk_bf16_f32 v222, v206, v207
	v_cvt_pk_bf16_f32 v223, v208, v209
	v_cvt_pk_bf16_f32 v224, v210, v211
	v_cvt_pk_bf16_f32 v225, v212, v213
	global_store_dwordx4 v249, v[222:225], s[38:39]
	v_cvt_pk_bf16_f32 v228, v214, v215
	v_cvt_pk_bf16_f32 v229, v216, v217
	v_cvt_pk_bf16_f32 v230, v218, v219
	v_cvt_pk_bf16_f32 v231, v220, v221
	global_store_dwordx4 v249, v[228:231], s[38:39] offset:256
	s_cmp_eq_u32 s22, 0
	s_cbranch_scc1 .Lp3_noan_0_7
	v_pk_mul_f32 v[206:207], v[206:207], v[62:63]
	v_pk_mul_f32 v[208:209], v[208:209], v[64:65]
	v_pk_mul_f32 v[210:211], v[210:211], v[70:71]
	v_pk_mul_f32 v[212:213], v[212:213], v[72:73]
	v_cvt_pk_bf16_f32 v222, v206, v207
	v_cvt_pk_bf16_f32 v223, v208, v209
	v_cvt_pk_bf16_f32 v224, v210, v211
	v_cvt_pk_bf16_f32 v225, v212, v213
	v_pk_mul_f32 v[214:215], v[214:215], v[74:75]
	v_pk_mul_f32 v[216:217], v[216:217], v[76:77]
	v_pk_mul_f32 v[218:219], v[218:219], v[78:79]
	v_pk_mul_f32 v[220:221], v[220:221], v[80:81]
	v_cvt_pk_bf16_f32 v228, v214, v215
	v_cvt_pk_bf16_f32 v229, v216, v217
	v_cvt_pk_bf16_f32 v230, v218, v219
	v_cvt_pk_bf16_f32 v231, v220, v221
	v_add_u32_e32 v243, 0x4400000, v249
	global_store_dwordx4 v243, v[222:225], s[38:39]
	global_store_dwordx4 v243, v[228:231], s[38:39] offset:256
.Lp3_noan_0_7:
.Lp3_join:
	ds_bpermute_b32 v164, v246, v190
	ds_bpermute_b32 v165, v246, v192
	ds_bpermute_b32 v166, v246, v226
	ds_bpermute_b32 v167, v246, v236
	ds_bpermute_b32 v168, v246, v239
	ds_bpermute_b32 v169, v246, v252
	ds_bpermute_b32 v170, v246, v251
	ds_bpermute_b32 v171, v246, v250
	s_waitcnt lgkmcnt(7)
	v_add_f32_e32 v190, v190, v164
	s_waitcnt lgkmcnt(6)
	v_add_f32_e32 v192, v192, v165
	s_waitcnt lgkmcnt(5)
	v_add_f32_e32 v226, v226, v166
	s_waitcnt lgkmcnt(4)
	v_add_f32_e32 v236, v236, v167
	s_waitcnt lgkmcnt(3)
	v_add_f32_e32 v239, v239, v168
	s_waitcnt lgkmcnt(2)
	v_add_f32_e32 v252, v252, v169
	s_waitcnt lgkmcnt(1)
	v_add_f32_e32 v251, v251, v170
	s_waitcnt lgkmcnt(0)
	v_add_f32_e32 v250, v250, v171
	ds_bpermute_b32 v164, v245, v190
	ds_bpermute_b32 v165, v245, v192
	ds_bpermute_b32 v166, v245, v226
	ds_bpermute_b32 v167, v245, v236
	ds_bpermute_b32 v168, v245, v239
	ds_bpermute_b32 v169, v245, v252
	ds_bpermute_b32 v170, v245, v251
	ds_bpermute_b32 v171, v245, v250
	s_waitcnt lgkmcnt(7)
	v_add_f32_e32 v190, v190, v164
	s_waitcnt lgkmcnt(6)
	v_add_f32_e32 v192, v192, v165
	s_waitcnt lgkmcnt(5)
	v_add_f32_e32 v226, v226, v166
	s_waitcnt lgkmcnt(4)
	v_add_f32_e32 v236, v236, v167
	s_waitcnt lgkmcnt(3)
	v_add_f32_e32 v239, v239, v168
	s_waitcnt lgkmcnt(2)
	v_add_f32_e32 v252, v252, v169
	s_waitcnt lgkmcnt(1)
	v_add_f32_e32 v251, v251, v170
	s_waitcnt lgkmcnt(0)
	v_add_f32_e32 v250, v250, v171
	s_mul_i32 s16, s73, 0x22000
	s_lshr_b32 s4, s77, 3
	s_add_u32 s16, s16, s4
	s_add_u32 s16, s16, 0x6700000
	v_lshl_add_u32 v243, v244, 4, s16
	s_mov_b64 exec, 0xffff
	global_store_dword v243, v190, s[38:39]
	global_store_dword v243, v192, s[38:39] offset:256
	global_store_dword v243, v226, s[38:39] offset:512
	global_store_dword v243, v236, s[38:39] offset:768
	global_store_dword v243, v239, s[38:39] offset:2048
	global_store_dword v243, v252, s[38:39] offset:2304
	global_store_dword v243, v251, s[38:39] offset:2560
	global_store_dword v243, v250, s[38:39] offset:2816
	s_mov_b64 exec, -1
	s_waitcnt lgkmcnt(0)
	v_xor_b32_e32 v162, 16, v201
	v_lshlrev_b32_e32 v162, 2, v162
	v_mov_b32_e32 v163, 64
	v_cmp_eq_u32_e64 s[42:43], 0, v194
	s_andn2_b64 vcc, exec, s[36:37]
	s_mov_b64 s[36:37], -1
	s_cbranch_vccnz .LBB0_893
	s_andn2_b64 vcc, exec, s[54:55]
	s_cbranch_vccnz .LBB0_892
	s_barrier
	s_branch .LBB0_892

; __device__ __forceinline__ unsigned pk2(float lo, float hi) { unsigned r; asm("v_cvt_pk_bf16_f32 %0, %1, %2" : "=v"(r) : "v"(lo), "v"(hi)); return r; }
;     __device__ __forceinline__ void operator()(const f32x4 (&acc)[2][2][4][2], const Unit& u, int wr, int wc, int fr_, int fq_) const {
;         int fr = fr_, fq = fq_; asm volatile("" : "+v"(fr), "+v"(fq));
;         const int row0 = u.pm * BM + wr * 64 + fr, v = vec_of_panel(u.pm);
;         const int colb = u.pn * BM + wc * 32 + 8 * fq;
;         f32x4 gt[2][2], gn[2][2];
; #pragma unroll
;         for (int bj = 0; bj < 2; ++bj)
; #pragma unroll
;             for (int n = 0; n < 2; ++n) { gt[bj][n] = *(const f32x4*)(gate + (size_t)v * 6 * D + colb + bj * HALF + 4 * n);
;                 gn[bj][n] = gnext ? *(const f32x4*)(gnext + (size_t)v * D + colb + bj * HALF + 4 * n) : (f32x4){0.f, 0.f, 0.f, 0.f}; }
; #pragma unroll
;         for (int ai = 0; ai < 2; ++ai)
; #pragma unroll
;             for (int m = 0; m < 4; ++m) { const int row = row0 + ai * HALF + m * 16;
;                 const size_t eo = (size_t)row * D + colb; float s = 0.f;
; #pragma unroll
;                 for (int bj = 0; bj < 2; ++bj) { f32x4 x[2];
;                     if (Xin) { x[0] = *(const f32x4*)(Xin + eo + bj * HALF); x[1] = *(const f32x4*)(Xin + eo + bj * HALF + 4); }
;                     else { const u32x4 xw = *(const u32x4*)(Xb + eo + bj * HALF); x[0] = (f32x4){bf_lo(xw.x), bf_hi(xw.x), bf_lo(xw.y), bf_hi(xw.y)}; x[1] = (f32x4){bf_lo(xw.z), bf_hi(xw.z), bf_lo(xw.w), bf_hi(xw.w)}; }
; #pragma unroll
;                     for (int n = 0; n < 2; ++n) { x[n] = x[n] + gt[bj][n] * acc[ai][bj][m][n];
;                         s += (x[n][0] * x[n][0] + x[n][1] * x[n][1]) + (x[n][2] * x[n][2] + x[n][3] * x[n][3]); }
;                     if (live) { u32x4 xo; xo.x = pk2(x[0][0], x[0][1]); xo.y = pk2(x[0][2], x[0][3]); xo.z = pk2(x[1][0], x[1][1]); xo.w = pk2(x[1][2], x[1][3]); *(u32x4*)(X + eo + bj * HALF) = xo; }
;                     if (gnext && live) { const f32x4 a = x[0] * gn[bj][0], b = x[1] * gn[bj][1];
;                         u32x4 w; w.x = pk2(a[0], a[1]); w.y = pk2(a[2], a[3]); w.z = pk2(b[0], b[1]); w.w = pk2(b[2], b[3]);
;                         *(u32x4*)(AN + (size_t)row * D + colb + bj * HALF) = w; } }
.LBB0_1351:
	v_readlane_b32 s12, v253, 3
	v_readlane_b32 s13, v253, 4
	v_readlane_b32 s24, v255, 28
	s_lshl_b32 s4, s90, 8
	s_add_u32 s4, s4, s72
	v_add_u32_e32 v244, s4, v185
	s_nop 0
	s_load_dwordx2 s[40:41], s[12:13], 0xd8
	s_lshl_b32 s7, s89, 8
	s_add_u32 s7, s7, s73
	v_lshl_add_u32 v243, v184, 3, s7
	v_lshl_add_u32 v249, v244, 11, v243
	s_cmp_ge_u32 s90, 16
	s_cselect_b32 s14, 1, 0
	s_mul_i32 s16, s24, 0x6000
	s_mul_i32 s4, s14, 0xc000
	s_add_u32 s16, s16, s4
	s_add_u32 s16, s16, 0x15aaa000
	v_lshlrev_b32_e32 v248, 2, v243
	v_add_u32_e32 v248, s16, v248
	s_mul_i32 s16, s24, 0x2000
	s_mul_i32 s4, s14, 0x2000
	s_add_u32 s16, s16, s4
	s_add_u32 s16, s16, 0x15b84000
	v_lshlrev_b32_e32 v247, 2, v243
	v_add_u32_e32 v247, s16, v247
	s_cmp_lt_u32 s24, 18
	s_cselect_b32 s22, 1, 0
	v_xor_b32_e32 v246, 16, v201
	v_lshlrev_b32_e32 v246, 2, v246
	v_xor_b32_e32 v245, 32, v201
	v_lshlrev_b32_e32 v245, 2, v245
	s_waitcnt lgkmcnt(0)
	global_load_dwordx4 v[62:65], v248, s[40:41]
	global_load_dwordx4 v[70:73], v248, s[40:41] offset:16
	global_load_dwordx4 v[74:77], v248, s[40:41] offset:512
	global_load_dwordx4 v[78:81], v248, s[40:41] offset:528
	global_load_dwordx4 v[82:85], v247, s[40:41]
	global_load_dwordx4 v[86:89], v247, s[40:41] offset:16
	global_load_dwordx4 v[90:93], v247, s[40:41] offset:512
	global_load_dwordx4 v[94:97], v247, s[40:41] offset:528
	v_lshlrev_b32_e32 v242, 1, v249
	v_add_u32_e32 v242, 0x100000, v242
	v_lshlrev_b32_e32 v249, 1, v249
	v_add_u32_e32 v249, 0x100000, v249
	global_load_dwordx4 v[170:173], v242, s[40:41]
	global_load_dwordx4 v[176:179], v242, s[40:41] offset:256
	v_add_u32_e32 v242, 0x10000, v242
	global_load_dwordx4 v[180:183], v242, s[40:41]
	global_load_dwordx4 v[202:205], v242, s[40:41] offset:256
	v_add_u32_e32 v242, 0x10000, v242
	s_waitcnt vmcnt(3)
	v_and_b32_e32 v207, 0xffff0000, v170
	v_lshlrev_b32_e32 v206, 16, v170
	v_and_b32_e32 v209, 0xffff0000, v171
	v_lshlrev_b32_e32 v208, 16, v171
	v_and_b32_e32 v211, 0xffff0000, v172
	v_lshlrev_b32_e32 v210, 16, v172
	v_and_b32_e32 v213, 0xffff0000, v173
	v_lshlrev_b32_e32 v212, 16, v173
	s_waitcnt vmcnt(2)
	v_and_b32_e32 v215, 0xffff0000, v176
	v_lshlrev_b32_e32 v214, 16, v176
	v_and_b32_e32 v217, 0xffff0000, v177
	v_lshlrev_b32_e32 v216, 16, v177
	v_and_b32_e32 v219, 0xffff0000, v178
	v_lshlrev_b32_e32 v218, 16, v178
	v_and_b32_e32 v221, 0xffff0000, v179
	v_lshlrev_b32_e32 v220, 16, v179
	global_load_dwordx4 v[170:173], v242, s[40:41]
	global_load_dwordx4 v[176:179], v242, s[40:41] offset:256
	v_add_u32_e32 v242, 0x10000, v242
	v_pk_fma_f32 v[206:207], v[62:63], v[158:159], v[206:207]
	v_pk_fma_f32 v[208:209], v[64:65], v[160:161], v[208:209]
	v_pk_fma_f32 v[210:211], v[70:71], v[154:155], v[210:211]
	v_pk_fma_f32 v[212:213], v[72:73], v[156:157], v[212:213]
	v_pk_fma_f32 v[214:215], v[74:75], v[150:151], v[214:215]
	v_pk_fma_f32 v[216:217], v[76:77], v[152:153], v[216:217]
	v_pk_fma_f32 v[218:219], v[78:79], v[146:147], v[218:219]
	v_pk_fma_f32 v[220:221], v[80:81], v[148:149], v[220:221]
	v_pk_mul_f32 v[188:189], v[206:207], v[206:207]
	v_pk_fma_f32 v[188:189], v[208:209], v[208:209], v[188:189]
	v_pk_fma_f32 v[188:189], v[210:211], v[210:211], v[188:189]
	v_pk_fma_f32 v[188:189], v[212:213], v[212:213], v[188:189]
	v_pk_fma_f32 v[188:189], v[214:215], v[214:215], v[188:189]
	v_pk_fma_f32 v[188:189], v[216:217], v[216:217], v[188:189]
	v_pk_fma_f32 v[188:189], v[218:219], v[218:219], v[188:189]
	v_pk_fma_f32 v[188:189], v[220:221], v[220:221], v[188:189]
	v_add_f32_e32 v190, v188, v189
	v_cvt_pk_bf16_f32 v222, v206, v207
	v_cvt_pk_bf16_f32 v223, v208, v209
	v_cvt_pk_bf16_f32 v224, v210, v211
	v_cvt_pk_bf16_f32 v225, v212, v213
	global_store_dwordx4 v249, v[222:225], s[40:41]
	v_cvt_pk_bf16_f32 v228, v214, v215
	v_cvt_pk_bf16_f32 v229, v216, v217
	v_cvt_pk_bf16_f32 v230, v218, v219
	v_cvt_pk_bf16_f32 v231, v220, v221
	global_store_dwordx4 v249, v[228:231], s[40:41] offset:256
	s_cmp_eq_u32 s22, 0
	s_cbranch_scc1 .Lp5_noan_0_0
	v_pk_mul_f32 v[206:207], v[206:207], v[82:83]
	v_pk_mul_f32 v[208:209], v[208:209], v[84:85]
	v_pk_mul_f32 v[210:211], v[210:211], v[86:87]
	v_pk_mul_f32 v[212:213], v[212:213], v[88:89]
	v_cvt_pk_bf16_f32 v222, v206, v207
	v_cvt_pk_bf16_f32 v223, v208, v209
	v_cvt_pk_bf16_f32 v224, v210, v211
	v_cvt_pk_bf16_f32 v225, v212, v213
	v_pk_mul_f32 v[214:215], v[214:215], v[90:91]
	v_pk_mul_f32 v[216:217], v[216:217], v[92:93]
	v_pk_mul_f32 v[218:219], v[218:219], v[94:95]
	v_pk_mul_f32 v[220:221], v[220:221], v[96:97]
	v_cvt_pk_bf16_f32 v228, v214, v215
	v_cvt_pk_bf16_f32 v229, v216, v217
	v_cvt_pk_bf16_f32 v230, v218, v219
	v_cvt_pk_bf16_f32 v231, v220, v221
	v_add_u32_e32 v243, 0x4400000, v249
	global_store_dwordx4 v243, v[222:225], s[40:41]
	global_store_dwordx4 v243, v[228:231], s[40:41] offset:256
; __device__ __forceinline__ unsigned pk2(float lo, float hi) { unsigned r; asm("v_cvt_pk_bf16_f32 %0, %1, %2" : "=v"(r) : "v"(lo), "v"(hi)); return r; }
;     __device__ __forceinline__ void operator()(const f32x4 (&acc)[2][2][4][2], const Unit& u, int wr, int wc, int fr_, int fq_) const {
;     ...
;             for (int m = 0; m < 4; ++m) { const int row = row0 + ai * HALF + m * 16;
;                 const size_t eo = (size_t)row * D + colb; float s = 0.f;
; #pragma unroll
;                 for (int bj = 0; bj < 2; ++bj) { f32x4 x[2];
;                     if (Xin) { x[0] = *(const f32x4*)(Xin + eo + bj * HALF); x[1] = *(const f32x4*)(Xin + eo + bj * HALF + 4); }
;                     else { const u32x4 xw = *(const u32x4*)(Xb + eo + bj * HALF); x[0] = (f32x4){bf_lo(xw.x), bf_hi(xw.x), bf_lo(xw.y), bf_hi(xw.y)}; x[1] = (f32x4){bf_lo(xw.z), bf_hi(xw.z), bf_lo(xw.w), bf_hi(xw.w)}; }
; #pragma unroll
;                     for (int n = 0; n < 2; ++n) { x[n] = x[n] + gt[bj][n] * acc[ai][bj][m][n];
;                         s += (x[n][0] * x[n][0] + x[n][1] * x[n][1]) + (x[n][2] * x[n][2] + x[n][3] * x[n][3]); }
;                     if (live) { u32x4 xo; xo.x = pk2(x[0][0], x[0][1]); xo.y = pk2(x[0][2], x[0][3]); xo.z = pk2(x[1][0], x[1][1]); xo.w = pk2(x[1][2], x[1][3]); *(u32x4*)(X + eo + bj * HALF) = xo; }
;                     if (gnext && live) { const f32x4 a = x[0] * gn[bj][0], b = x[1] * gn[bj][1];
;                         u32x4 w; w.x = pk2(a[0], a[1]); w.y = pk2(a[2], a[3]); w.z = pk2(b[0], b[1]); w.w = pk2(b[2], b[3]);
;                         *(u32x4*)(AN + (size_t)row * D + colb + bj * HALF) = w; } }
.Lp5_noan_0_0:
	v_add_u32_e32 v249, 0x10000, v249
	s_waitcnt vmcnt(5)
	v_and_b32_e32 v207, 0xffff0000, v180
	v_lshlrev_b32_e32 v206, 16, v180
	v_and_b32_e32 v209, 0xffff0000, v181
	v_lshlrev_b32_e32 v208, 16, v181
	v_and_b32_e32 v211, 0xffff0000, v182
	v_lshlrev_b32_e32 v210, 16, v182
	v_and_b32_e32 v213, 0xffff0000, v183
	v_lshlrev_b32_e32 v212, 16, v183
	s_waitcnt vmcnt(4)
	v_and_b32_e32 v215, 0xffff0000, v202
	v_lshlrev_b32_e32 v214, 16, v202
	v_and_b32_e32 v217, 0xffff0000, v203
	v_lshlrev_b32_e32 v216, 16, v203
	v_and_b32_e32 v219, 0xffff0000, v204
	v_lshlrev_b32_e32 v218, 16, v204
	v_and_b32_e32 v221, 0xffff0000, v205
	v_lshlrev_b32_e32 v220, 16, v205
	global_load_dwordx4 v[180:183], v242, s[40:41]
	global_load_dwordx4 v[202:205], v242, s[40:41] offset:256
	v_add_u32_e32 v242, 0x50000, v242
	v_pk_fma_f32 v[206:207], v[62:63], v[142:143], v[206:207]
	v_pk_fma_f32 v[208:209], v[64:65], v[144:145], v[208:209]
	v_pk_fma_f32 v[210:211], v[70:71], v[138:139], v[210:211]
	v_pk_fma_f32 v[212:213], v[72:73], v[140:141], v[212:213]
	v_pk_fma_f32 v[214:215], v[74:75], v[134:135], v[214:215]
	v_pk_fma_f32 v[216:217], v[76:77], v[136:137], v[216:217]
	v_pk_fma_f32 v[218:219], v[78:79], v[130:131], v[218:219]
	v_pk_fma_f32 v[220:221], v[80:81], v[132:133], v[220:221]
	v_pk_mul_f32 v[188:189], v[206:207], v[206:207]
	v_pk_fma_f32 v[188:189], v[208:209], v[208:209], v[188:189]
	v_pk_fma_f32 v[188:189], v[210:211], v[210:211], v[188:189]
	v_pk_fma_f32 v[188:189], v[212:213], v[212:213], v[188:189]
	v_pk_fma_f32 v[188:189], v[214:215], v[214:215], v[188:189]
	v_pk_fma_f32 v[188:189], v[216:217], v[216:217], v[188:189]
	v_pk_fma_f32 v[188:189], v[218:219], v[218:219], v[188:189]
	v_pk_fma_f32 v[188:189], v[220:221], v[220:221], v[188:189]
	v_add_f32_e32 v192, v188, v189
	v_cvt_pk_bf16_f32 v222, v206, v207
	v_cvt_pk_bf16_f32 v223, v208, v209
	v_cvt_pk_bf16_f32 v224, v210, v211
	v_cvt_pk_bf16_f32 v225, v212, v213
	global_store_dwordx4 v249, v[222:225], s[40:41]
	v_cvt_pk_bf16_f32 v228, v214, v215
	v_cvt_pk_bf16_f32 v229, v216, v217
	v_cvt_pk_bf16_f32 v230, v218, v219
	v_cvt_pk_bf16_f32 v231, v220, v221
	global_store_dwordx4 v249, v[228:231], s[40:41] offset:256
	s_cmp_eq_u32 s22, 0
	s_cbranch_scc1 .Lp5_noan_0_1
	v_pk_mul_f32 v[206:207], v[206:207], v[82:83]
	v_pk_mul_f32 v[208:209], v[208:209], v[84:85]
	v_pk_mul_f32 v[210:211], v[210:211], v[86:87]
	v_pk_mul_f32 v[212:213], v[212:213], v[88:89]
	v_cvt_pk_bf16_f32 v222, v206, v207
	v_cvt_pk_bf16_f32 v223, v208, v209
	v_cvt_pk_bf16_f32 v224, v210, v211
	v_cvt_pk_bf16_f32 v225, v212, v213
	v_pk_mul_f32 v[214:215], v[214:215], v[90:91]
	v_pk_mul_f32 v[216:217], v[216:217], v[92:93]
	v_pk_mul_f32 v[218:219], v[218:219], v[94:95]
	v_pk_mul_f32 v[220:221], v[220:221], v[96:97]
	v_cvt_pk_bf16_f32 v228, v214, v215
	v_cvt_pk_bf16_f32 v229, v216, v217
	v_cvt_pk_bf16_f32 v230, v218, v219
	v_cvt_pk_bf16_f32 v231, v220, v221
	v_add_u32_e32 v243, 0x4400000, v249
	global_store_dwordx4 v243, v[222:225], s[40:41]
	global_store_dwordx4 v243, v[228:231], s[40:41] offset:256
.Lp5_noan_0_1:
	v_add_u32_e32 v249, 0x10000, v249
	s_waitcnt vmcnt(7)
	v_and_b32_e32 v207, 0xffff0000, v170
	v_lshlrev_b32_e32 v206, 16, v170
	v_and_b32_e32 v209, 0xffff0000, v171
	v_lshlrev_b32_e32 v208, 16, v171
	v_and_b32_e32 v211, 0xffff0000, v172
	v_lshlrev_b32_e32 v210, 16, v172
	v_and_b32_e32 v213, 0xffff0000, v173
	v_lshlrev_b32_e32 v212, 16, v173
	s_waitcnt vmcnt(6)
	v_and_b32_e32 v215, 0xffff0000, v176
	v_lshlrev_b32_e32 v214, 16, v176
	v_and_b32_e32 v217, 0xffff0000, v177
	v_lshlrev_b32_e32 v216, 16, v177
	v_and_b32_e32 v219, 0xffff0000, v178
	v_lshlrev_b32_e32 v218, 16, v178
	v_and_b32_e32 v221, 0xffff0000, v179
	v_lshlrev_b32_e32 v220, 16, v179
	global_load_dwordx4 v[170:173], v242, s[40:41]
	global_load_dwordx4 v[176:179], v242, s[40:41] offset:256
	v_add_u32_e32 v242, 0x10000, v242
	v_pk_fma_f32 v[206:207], v[62:63], v[126:127], v[206:207]
	v_pk_fma_f32 v[208:209], v[64:65], v[128:129], v[208:209]
	v_pk_fma_f32 v[210:211], v[70:71], v[122:123], v[210:211]
	v_pk_fma_f32 v[212:213], v[72:73], v[124:125], v[212:213]
	v_pk_fma_f32 v[214:215], v[74:75], v[118:119], v[214:215]
	v_pk_fma_f32 v[216:217], v[76:77], v[120:121], v[216:217]
	v_pk_fma_f32 v[218:219], v[78:79], v[114:115], v[218:219]
	v_pk_fma_f32 v[220:221], v[80:81], v[116:117], v[220:221]
	v_pk_mul_f32 v[188:189], v[206:207], v[206:207]
	v_pk_fma_f32 v[188:189], v[208:209], v[208:209], v[188:189]
	v_pk_fma_f32 v[188:189], v[210:211], v[210:211], v[188:189]
	v_pk_fma_f32 v[188:189], v[212:213], v[212:213], v[188:189]
	v_pk_fma_f32 v[188:189], v[214:215], v[214:215], v[188:189]
	v_pk_fma_f32 v[188:189], v[216:217], v[216:217], v[188:189]
	v_pk_fma_f32 v[188:189], v[218:219], v[218:219], v[188:189]
	v_pk_fma_f32 v[188:189], v[220:221], v[220:221], v[188:189]
	v_add_f32_e32 v226, v188, v189
	v_cvt_pk_bf16_f32 v222, v206, v207
	v_cvt_pk_bf16_f32 v223, v208, v209
	v_cvt_pk_bf16_f32 v224, v210, v211
	v_cvt_pk_bf16_f32 v225, v212, v213
	global_store_dwordx4 v249, v[222:225], s[40:41]
	v_cvt_pk_bf16_f32 v228, v214, v215
	v_cvt_pk_bf16_f32 v229, v216, v217
	v_cvt_pk_bf16_f32 v230, v218, v219
	v_cvt_pk_bf16_f32 v231, v220, v221
	global_store_dwordx4 v249, v[228:231], s[40:41] offset:256
	s_cmp_eq_u32 s22, 0
	s_cbranch_scc1 .Lp5_noan_0_2
	v_pk_mul_f32 v[206:207], v[206:207], v[82:83]
	v_pk_mul_f32 v[208:209], v[208:209], v[84:85]
	v_pk_mul_f32 v[210:211], v[210:211], v[86:87]
	v_pk_mul_f32 v[212:213], v[212:213], v[88:89]
	v_cvt_pk_bf16_f32 v222, v206, v207
	v_cvt_pk_bf16_f32 v223, v208, v209
	v_cvt_pk_bf16_f32 v224, v210, v211
	v_cvt_pk_bf16_f32 v225, v212, v213
	v_pk_mul_f32 v[214:215], v[214:215], v[90:91]
	v_pk_mul_f32 v[216:217], v[216:217], v[92:93]
	v_pk_mul_f32 v[218:219], v[218:219], v[94:95]
	v_pk_mul_f32 v[220:221], v[220:221], v[96:97]
	v_cvt_pk_bf16_f32 v228, v214, v215
	v_cvt_pk_bf16_f32 v229, v216, v217
	v_cvt_pk_bf16_f32 v230, v218, v219
	v_cvt_pk_bf16_f32 v231, v220, v221
	v_add_u32_e32 v243, 0x4400000, v249
	global_store_dwordx4 v243, v[222:225], s[40:41]
	global_store_dwordx4 v243, v[228:231], s[40:41] offset:256
; __device__ __forceinline__ unsigned pk2(float lo, float hi) { unsigned r; asm("v_cvt_pk_bf16_f32 %0, %1, %2" : "=v"(r) : "v"(lo), "v"(hi)); return r; }
;     __device__ __forceinline__ void operator()(const f32x4 (&acc)[2][2][4][2], const Unit& u, int wr, int wc, int fr_, int fq_) const {
;     ...
;             for (int m = 0; m < 4; ++m) { const int row = row0 + ai * HALF + m * 16;
;                 const size_t eo = (size_t)row * D + colb; float s = 0.f;
; #pragma unroll
;                 for (int bj = 0; bj < 2; ++bj) { f32x4 x[2];
;                     if (Xin) { x[0] = *(const f32x4*)(Xin + eo + bj * HALF); x[1] = *(const f32x4*)(Xin + eo + bj * HALF + 4); }
;                     else { const u32x4 xw = *(const u32x4*)(Xb + eo + bj * HALF); x[0] = (f32x4){bf_lo(xw.x), bf_hi(xw.x), bf_lo(xw.y), bf_hi(xw.y)}; x[1] = (f32x4){bf_lo(xw.z), bf_hi(xw.z), bf_lo(xw.w), bf_hi(xw.w)}; }
; #pragma unroll
;                     for (int n = 0; n < 2; ++n) { x[n] = x[n] + gt[bj][n] * acc[ai][bj][m][n];
;                         s += (x[n][0] * x[n][0] + x[n][1] * x[n][1]) + (x[n][2] * x[n][2] + x[n][3] * x[n][3]); }
;                     if (live) { u32x4 xo; xo.x = pk2(x[0][0], x[0][1]); xo.y = pk2(x[0][2], x[0][3]); xo.z = pk2(x[1][0], x[1][1]); xo.w = pk2(x[1][2], x[1][3]); *(u32x4*)(X + eo + bj * HALF) = xo; }
;                     if (gnext && live) { const f32x4 a = x[0] * gn[bj][0], b = x[1] * gn[bj][1];
;                         u32x4 w; w.x = pk2(a[0], a[1]); w.y = pk2(a[2], a[3]); w.z = pk2(b[0], b[1]); w.w = pk2(b[2], b[3]);
;                         *(u32x4*)(AN + (size_t)row * D + colb + bj * HALF) = w; } }
.Lp5_noan_0_2:
	v_add_u32_e32 v249, 0x10000, v249
	s_waitcnt vmcnt(7)
	v_and_b32_e32 v207, 0xffff0000, v180
	v_lshlrev_b32_e32 v206, 16, v180
	v_and_b32_e32 v209, 0xffff0000, v181
	v_lshlrev_b32_e32 v208, 16, v181
	v_and_b32_e32 v211, 0xffff0000, v182
	v_lshlrev_b32_e32 v210, 16, v182
	v_and_b32_e32 v213, 0xffff0000, v183
	v_lshlrev_b32_e32 v212, 16, v183
	s_waitcnt vmcnt(6)
	v_and_b32_e32 v215, 0xffff0000, v202
	v_lshlrev_b32_e32 v214, 16, v202
	v_and_b32_e32 v217, 0xffff0000, v203
	v_lshlrev_b32_e32 v216, 16, v203
	v_and_b32_e32 v219, 0xffff0000, v204
	v_lshlrev_b32_e32 v218, 16, v204
	v_and_b32_e32 v221, 0xffff0000, v205
	v_lshlrev_b32_e32 v220, 16, v205
	global_load_dwordx4 v[180:183], v242, s[40:41]
	global_load_dwordx4 v[202:205], v242, s[40:41] offset:256
	v_add_u32_e32 v242, 0x10000, v242
	v_pk_fma_f32 v[206:207], v[62:63], v[110:111], v[206:207]
	v_pk_fma_f32 v[208:209], v[64:65], v[112:113], v[208:209]
	v_pk_fma_f32 v[210:211], v[70:71], v[106:107], v[210:211]
	v_pk_fma_f32 v[212:213], v[72:73], v[108:109], v[212:213]
	v_pk_fma_f32 v[214:215], v[74:75], v[102:103], v[214:215]
	v_pk_fma_f32 v[216:217], v[76:77], v[104:105], v[216:217]
	v_pk_fma_f32 v[218:219], v[78:79], v[98:99], v[218:219]
	v_pk_fma_f32 v[220:221], v[80:81], v[100:101], v[220:221]
	v_pk_mul_f32 v[188:189], v[206:207], v[206:207]
	v_pk_fma_f32 v[188:189], v[208:209], v[208:209], v[188:189]
	v_pk_fma_f32 v[188:189], v[210:211], v[210:211], v[188:189]
	v_pk_fma_f32 v[188:189], v[212:213], v[212:213], v[188:189]
	v_pk_fma_f32 v[188:189], v[214:215], v[214:215], v[188:189]
	v_pk_fma_f32 v[188:189], v[216:217], v[216:217], v[188:189]
	v_pk_fma_f32 v[188:189], v[218:219], v[218:219], v[188:189]
	v_pk_fma_f32 v[188:189], v[220:221], v[220:221], v[188:189]
	v_add_f32_e32 v236, v188, v189
	v_cvt_pk_bf16_f32 v222, v206, v207
	v_cvt_pk_bf16_f32 v223, v208, v209
	v_cvt_pk_bf16_f32 v224, v210, v211
	v_cvt_pk_bf16_f32 v225, v212, v213
	global_store_dwordx4 v249, v[222:225], s[40:41]
	v_cvt_pk_bf16_f32 v228, v214, v215
	v_cvt_pk_bf16_f32 v229, v216, v217
	v_cvt_pk_bf16_f32 v230, v218, v219
	v_cvt_pk_bf16_f32 v231, v220, v221
	global_store_dwordx4 v249, v[228:231], s[40:41] offset:256
	s_cmp_eq_u32 s22, 0
	s_cbranch_scc1 .Lp5_noan_0_3
	v_pk_mul_f32 v[206:207], v[206:207], v[82:83]
	v_pk_mul_f32 v[208:209], v[208:209], v[84:85]
	v_pk_mul_f32 v[210:211], v[210:211], v[86:87]
	v_pk_mul_f32 v[212:213], v[212:213], v[88:89]
	v_cvt_pk_bf16_f32 v222, v206, v207
	v_cvt_pk_bf16_f32 v223, v208, v209
	v_cvt_pk_bf16_f32 v224, v210, v211
	v_cvt_pk_bf16_f32 v225, v212, v213
	v_pk_mul_f32 v[214:215], v[214:215], v[90:91]
	v_pk_mul_f32 v[216:217], v[216:217], v[92:93]
	v_pk_mul_f32 v[218:219], v[218:219], v[94:95]
	v_pk_mul_f32 v[220:221], v[220:221], v[96:97]
	v_cvt_pk_bf16_f32 v228, v214, v215
	v_cvt_pk_bf16_f32 v229, v216, v217
	v_cvt_pk_bf16_f32 v230, v218, v219
	v_cvt_pk_bf16_f32 v231, v220, v221
	v_add_u32_e32 v243, 0x4400000, v249
	global_store_dwordx4 v243, v[222:225], s[40:41]
	global_store_dwordx4 v243, v[228:231], s[40:41] offset:256
.Lp5_noan_0_3:
	v_add_u32_e32 v249, 0x50000, v249
	s_waitcnt vmcnt(7)
	v_and_b32_e32 v207, 0xffff0000, v170
	v_lshlrev_b32_e32 v206, 16, v170
	v_and_b32_e32 v209, 0xffff0000, v171
	v_lshlrev_b32_e32 v208, 16, v171
	v_and_b32_e32 v211, 0xffff0000, v172
	v_lshlrev_b32_e32 v210, 16, v172
	v_and_b32_e32 v213, 0xffff0000, v173
	v_lshlrev_b32_e32 v212, 16, v173
	s_waitcnt vmcnt(6)
	v_and_b32_e32 v215, 0xffff0000, v176
	v_lshlrev_b32_e32 v214, 16, v176
	v_and_b32_e32 v217, 0xffff0000, v177
	v_lshlrev_b32_e32 v216, 16, v177
	v_and_b32_e32 v219, 0xffff0000, v178
	v_lshlrev_b32_e32 v218, 16, v178
	v_and_b32_e32 v221, 0xffff0000, v179
	v_lshlrev_b32_e32 v220, 16, v179
	global_load_dwordx4 v[170:173], v242, s[40:41]
	global_load_dwordx4 v[176:179], v242, s[40:41] offset:256
	v_add_u32_e32 v242, 0x10000, v242
	v_pk_fma_f32 v[206:207], v[62:63], v[66:67], v[206:207]
	v_pk_fma_f32 v[208:209], v[64:65], v[68:69], v[208:209]
	v_pk_fma_f32 v[210:211], v[70:71], v[58:59], v[210:211]
	v_pk_fma_f32 v[212:213], v[72:73], v[60:61], v[212:213]
	v_pk_fma_f32 v[214:215], v[74:75], v[54:55], v[214:215]
	v_pk_fma_f32 v[216:217], v[76:77], v[56:57], v[216:217]
	v_pk_fma_f32 v[218:219], v[78:79], v[50:51], v[218:219]
	v_pk_fma_f32 v[220:221], v[80:81], v[52:53], v[220:221]
	v_pk_mul_f32 v[188:189], v[206:207], v[206:207]
	v_pk_fma_f32 v[188:189], v[208:209], v[208:209], v[188:189]
	v_pk_fma_f32 v[188:189], v[210:211], v[210:211], v[188:189]
	v_pk_fma_f32 v[188:189], v[212:213], v[212:213], v[188:189]
	v_pk_fma_f32 v[188:189], v[214:215], v[214:215], v[188:189]
	v_pk_fma_f32 v[188:189], v[216:217], v[216:217], v[188:189]
	v_pk_fma_f32 v[188:189], v[218:219], v[218:219], v[188:189]
	v_pk_fma_f32 v[188:189], v[220:221], v[220:221], v[188:189]
	v_add_f32_e32 v239, v188, v189
	v_cvt_pk_bf16_f32 v222, v206, v207
	v_cvt_pk_bf16_f32 v223, v208, v209
	v_cvt_pk_bf16_f32 v224, v210, v211
	v_cvt_pk_bf16_f32 v225, v212, v213
	global_store_dwordx4 v249, v[222:225], s[40:41]
	v_cvt_pk_bf16_f32 v228, v214, v215
	v_cvt_pk_bf16_f32 v229, v216, v217
	v_cvt_pk_bf16_f32 v230, v218, v219
	v_cvt_pk_bf16_f32 v231, v220, v221
	global_store_dwordx4 v249, v[228:231], s[40:41] offset:256
	s_cmp_eq_u32 s22, 0
	s_cbranch_scc1 .Lp5_noan_0_4
	v_pk_mul_f32 v[206:207], v[206:207], v[82:83]
	v_pk_mul_f32 v[208:209], v[208:209], v[84:85]
	v_pk_mul_f32 v[210:211], v[210:211], v[86:87]
	v_pk_mul_f32 v[212:213], v[212:213], v[88:89]
	v_cvt_pk_bf16_f32 v222, v206, v207
	v_cvt_pk_bf16_f32 v223, v208, v209
	v_cvt_pk_bf16_f32 v224, v210, v211
	v_cvt_pk_bf16_f32 v225, v212, v213
	v_pk_mul_f32 v[214:215], v[214:215], v[90:91]
	v_pk_mul_f32 v[216:217], v[216:217], v[92:93]
	v_pk_mul_f32 v[218:219], v[218:219], v[94:95]
	v_pk_mul_f32 v[220:221], v[220:221], v[96:97]
	v_cvt_pk_bf16_f32 v228, v214, v215
	v_cvt_pk_bf16_f32 v229, v216, v217
	v_cvt_pk_bf16_f32 v230, v218, v219
	v_cvt_pk_bf16_f32 v231, v220, v221
	v_add_u32_e32 v243, 0x4400000, v249
	global_store_dwordx4 v243, v[222:225], s[40:41]
	global_store_dwordx4 v243, v[228:231], s[40:41] offset:256
; __device__ __forceinline__ unsigned pk2(float lo, float hi) { unsigned r; asm("v_cvt_pk_bf16_f32 %0, %1, %2" : "=v"(r) : "v"(lo), "v"(hi)); return r; }
;     __device__ __forceinline__ void operator()(const f32x4 (&acc)[2][2][4][2], const Unit& u, int wr, int wc, int fr_, int fq_) const {
;     ...
;             for (int m = 0; m < 4; ++m) { const int row = row0 + ai * HALF + m * 16;
;                 const size_t eo = (size_t)row * D + colb; float s = 0.f;
; #pragma unroll
;                 for (int bj = 0; bj < 2; ++bj) { f32x4 x[2];
;                     if (Xin) { x[0] = *(const f32x4*)(Xin + eo + bj * HALF); x[1] = *(const f32x4*)(Xin + eo + bj * HALF + 4); }
;                     else { const u32x4 xw = *(const u32x4*)(Xb + eo + bj * HALF); x[0] = (f32x4){bf_lo(xw.x), bf_hi(xw.x), bf_lo(xw.y), bf_hi(xw.y)}; x[1] = (f32x4){bf_lo(xw.z), bf_hi(xw.z), bf_lo(xw.w), bf_hi(xw.w)}; }
; #pragma unroll
;                     for (int n = 0; n < 2; ++n) { x[n] = x[n] + gt[bj][n] * acc[ai][bj][m][n];
;                         s += (x[n][0] * x[n][0] + x[n][1] * x[n][1]) + (x[n][2] * x[n][2] + x[n][3] * x[n][3]); }
;                     if (live) { u32x4 xo; xo.x = pk2(x[0][0], x[0][1]); xo.y = pk2(x[0][2], x[0][3]); xo.z = pk2(x[1][0], x[1][1]); xo.w = pk2(x[1][2], x[1][3]); *(u32x4*)(X + eo + bj * HALF) = xo; }
;                     if (gnext && live) { const f32x4 a = x[0] * gn[bj][0], b = x[1] * gn[bj][1];
;                         u32x4 w; w.x = pk2(a[0], a[1]); w.y = pk2(a[2], a[3]); w.z = pk2(b[0], b[1]); w.w = pk2(b[2], b[3]);
;                         *(u32x4*)(AN + (size_t)row * D + colb + bj * HALF) = w; } }
.Lp5_noan_0_4:
	v_add_u32_e32 v249, 0x10000, v249
	s_waitcnt vmcnt(7)
	v_and_b32_e32 v207, 0xffff0000, v180
	v_lshlrev_b32_e32 v206, 16, v180
	v_and_b32_e32 v209, 0xffff0000, v181
	v_lshlrev_b32_e32 v208, 16, v181
	v_and_b32_e32 v211, 0xffff0000, v182
	v_lshlrev_b32_e32 v210, 16, v182
	v_and_b32_e32 v213, 0xffff0000, v183
	v_lshlrev_b32_e32 v212, 16, v183
	s_waitcnt vmcnt(6)
	v_and_b32_e32 v215, 0xffff0000, v202
	v_lshlrev_b32_e32 v214, 16, v202
	v_and_b32_e32 v217, 0xffff0000, v203
	v_lshlrev_b32_e32 v216, 16, v203
	v_and_b32_e32 v219, 0xffff0000, v204
	v_lshlrev_b32_e32 v218, 16, v204
	v_and_b32_e32 v221, 0xffff0000, v205
	v_lshlrev_b32_e32 v220, 16, v205
	global_load_dwordx4 v[180:183], v242, s[40:41]
	global_load_dwordx4 v[202:205], v242, s[40:41] offset:256
	v_pk_fma_f32 v[206:207], v[62:63], v[46:47], v[206:207]
	v_pk_fma_f32 v[208:209], v[64:65], v[48:49], v[208:209]
	v_pk_fma_f32 v[210:211], v[70:71], v[42:43], v[210:211]
	v_pk_fma_f32 v[212:213], v[72:73], v[44:45], v[212:213]
	v_pk_fma_f32 v[214:215], v[74:75], v[38:39], v[214:215]
	v_pk_fma_f32 v[216:217], v[76:77], v[40:41], v[216:217]
	v_pk_fma_f32 v[218:219], v[78:79], v[34:35], v[218:219]
	v_pk_fma_f32 v[220:221], v[80:81], v[36:37], v[220:221]
	v_pk_mul_f32 v[188:189], v[206:207], v[206:207]
	v_pk_fma_f32 v[188:189], v[208:209], v[208:209], v[188:189]
	v_pk_fma_f32 v[188:189], v[210:211], v[210:211], v[188:189]
	v_pk_fma_f32 v[188:189], v[212:213], v[212:213], v[188:189]
	v_pk_fma_f32 v[188:189], v[214:215], v[214:215], v[188:189]
	v_pk_fma_f32 v[188:189], v[216:217], v[216:217], v[188:189]
	v_pk_fma_f32 v[188:189], v[218:219], v[218:219], v[188:189]
	v_pk_fma_f32 v[188:189], v[220:221], v[220:221], v[188:189]
	v_add_f32_e32 v252, v188, v189
	v_cvt_pk_bf16_f32 v222, v206, v207
	v_cvt_pk_bf16_f32 v223, v208, v209
	v_cvt_pk_bf16_f32 v224, v210, v211
	v_cvt_pk_bf16_f32 v225, v212, v213
	global_store_dwordx4 v249, v[222:225], s[40:41]
	v_cvt_pk_bf16_f32 v228, v214, v215
	v_cvt_pk_bf16_f32 v229, v216, v217
	v_cvt_pk_bf16_f32 v230, v218, v219
	v_cvt_pk_bf16_f32 v231, v220, v221
	global_store_dwordx4 v249, v[228:231], s[40:41] offset:256
	s_cmp_eq_u32 s22, 0
	s_cbranch_scc1 .Lp5_noan_0_5
	v_pk_mul_f32 v[206:207], v[206:207], v[82:83]
	v_pk_mul_f32 v[208:209], v[208:209], v[84:85]
	v_pk_mul_f32 v[210:211], v[210:211], v[86:87]
	v_pk_mul_f32 v[212:213], v[212:213], v[88:89]
	v_cvt_pk_bf16_f32 v222, v206, v207
	v_cvt_pk_bf16_f32 v223, v208, v209
	v_cvt_pk_bf16_f32 v224, v210, v211
	v_cvt_pk_bf16_f32 v225, v212, v213
	v_pk_mul_f32 v[214:215], v[214:215], v[90:91]
	v_pk_mul_f32 v[216:217], v[216:217], v[92:93]
	v_pk_mul_f32 v[218:219], v[218:219], v[94:95]
	v_pk_mul_f32 v[220:221], v[220:221], v[96:97]
	v_cvt_pk_bf16_f32 v228, v214, v215
	v_cvt_pk_bf16_f32 v229, v216, v217
	v_cvt_pk_bf16_f32 v230, v218, v219
	v_cvt_pk_bf16_f32 v231, v220, v221
	v_add_u32_e32 v243, 0x4400000, v249
	global_store_dwordx4 v243, v[222:225], s[40:41]
	global_store_dwordx4 v243, v[228:231], s[40:41] offset:256
.Lp5_noan_0_5:
	v_add_u32_e32 v249, 0x10000, v249
	s_waitcnt vmcnt(7)
	v_and_b32_e32 v207, 0xffff0000, v170
	v_lshlrev_b32_e32 v206, 16, v170
	v_and_b32_e32 v209, 0xffff0000, v171
	v_lshlrev_b32_e32 v208, 16, v171
	v_and_b32_e32 v211, 0xffff0000, v172
	v_lshlrev_b32_e32 v210, 16, v172
	v_and_b32_e32 v213, 0xffff0000, v173
	v_lshlrev_b32_e32 v212, 16, v173
	s_waitcnt vmcnt(6)
	v_and_b32_e32 v215, 0xffff0000, v176
	v_lshlrev_b32_e32 v214, 16, v176
	v_and_b32_e32 v217, 0xffff0000, v177
	v_lshlrev_b32_e32 v216, 16, v177
	v_and_b32_e32 v219, 0xffff0000, v178
	v_lshlrev_b32_e32 v218, 16, v178
	v_and_b32_e32 v221, 0xffff0000, v179
	v_lshlrev_b32_e32 v220, 16, v179
	v_pk_fma_f32 v[206:207], v[62:63], v[30:31], v[206:207]
	v_pk_fma_f32 v[208:209], v[64:65], v[32:33], v[208:209]
	v_pk_fma_f32 v[210:211], v[70:71], v[26:27], v[210:211]
	v_pk_fma_f32 v[212:213], v[72:73], v[28:29], v[212:213]
	v_pk_fma_f32 v[214:215], v[74:75], v[22:23], v[214:215]
	v_pk_fma_f32 v[216:217], v[76:77], v[24:25], v[216:217]
	v_pk_fma_f32 v[218:219], v[78:79], v[18:19], v[218:219]
	v_pk_fma_f32 v[220:221], v[80:81], v[20:21], v[220:221]
	v_pk_mul_f32 v[188:189], v[206:207], v[206:207]
	v_pk_fma_f32 v[188:189], v[208:209], v[208:209], v[188:189]
	v_pk_fma_f32 v[188:189], v[210:211], v[210:211], v[188:189]
	v_pk_fma_f32 v[188:189], v[212:213], v[212:213], v[188:189]
	v_pk_fma_f32 v[188:189], v[214:215], v[214:215], v[188:189]
	v_pk_fma_f32 v[188:189], v[216:217], v[216:217], v[188:189]
	v_pk_fma_f32 v[188:189], v[218:219], v[218:219], v[188:189]
	v_pk_fma_f32 v[188:189], v[220:221], v[220:221], v[188:189]
	v_add_f32_e32 v251, v188, v189
	v_cvt_pk_bf16_f32 v222, v206, v207
	v_cvt_pk_bf16_f32 v223, v208, v209
	v_cvt_pk_bf16_f32 v224, v210, v211
	v_cvt_pk_bf16_f32 v225, v212, v213
	global_store_dwordx4 v249, v[222:225], s[40:41]
	v_cvt_pk_bf16_f32 v228, v214, v215
	v_cvt_pk_bf16_f32 v229, v216, v217
	v_cvt_pk_bf16_f32 v230, v218, v219
	v_cvt_pk_bf16_f32 v231, v220, v221
	global_store_dwordx4 v249, v[228:231], s[40:41] offset:256
	s_cmp_eq_u32 s22, 0
	s_cbranch_scc1 .Lp5_noan_0_6
	v_pk_mul_f32 v[206:207], v[206:207], v[82:83]
	v_pk_mul_f32 v[208:209], v[208:209], v[84:85]
	v_pk_mul_f32 v[210:211], v[210:211], v[86:87]
	v_pk_mul_f32 v[212:213], v[212:213], v[88:89]
	v_cvt_pk_bf16_f32 v222, v206, v207
	v_cvt_pk_bf16_f32 v223, v208, v209
	v_cvt_pk_bf16_f32 v224, v210, v211
	v_cvt_pk_bf16_f32 v225, v212, v213
	v_pk_mul_f32 v[214:215], v[214:215], v[90:91]
	v_pk_mul_f32 v[216:217], v[216:217], v[92:93]
	v_pk_mul_f32 v[218:219], v[218:219], v[94:95]
	v_pk_mul_f32 v[220:221], v[220:221], v[96:97]
	v_cvt_pk_bf16_f32 v228, v214, v215
	v_cvt_pk_bf16_f32 v229, v216, v217
	v_cvt_pk_bf16_f32 v230, v218, v219
	v_cvt_pk_bf16_f32 v231, v220, v221
	v_add_u32_e32 v243, 0x4400000, v249
	global_store_dwordx4 v243, v[222:225], s[40:41]
	global_store_dwordx4 v243, v[228:231], s[40:41] offset:256
; __device__ __forceinline__ unsigned pk2(float lo, float hi) { unsigned r; asm("v_cvt_pk_bf16_f32 %0, %1, %2" : "=v"(r) : "v"(lo), "v"(hi)); return r; }
;     __device__ __forceinline__ void operator()(const f32x4 (&acc)[2][2][4][2], const Unit& u, int wr, int wc, int fr_, int fq_) const {
;     ...
;                 for (int bj = 0; bj < 2; ++bj) { f32x4 x[2];
;                     if (Xin) { x[0] = *(const f32x4*)(Xin + eo + bj * HALF); x[1] = *(const f32x4*)(Xin + eo + bj * HALF + 4); }
;                     else { const u32x4 xw = *(const u32x4*)(Xb + eo + bj * HALF); x[0] = (f32x4){bf_lo(xw.x), bf_hi(xw.x), bf_lo(xw.y), bf_hi(xw.y)}; x[1] = (f32x4){bf_lo(xw.z), bf_hi(xw.z), bf_lo(xw.w), bf_hi(xw.w)}; }
; #pragma unroll
;                     for (int n = 0; n < 2; ++n) { x[n] = x[n] + gt[bj][n] * acc[ai][bj][m][n];
;                         s += (x[n][0] * x[n][0] + x[n][1] * x[n][1]) + (x[n][2] * x[n][2] + x[n][3] * x[n][3]); }
;                     if (live) { u32x4 xo; xo.x = pk2(x[0][0], x[0][1]); xo.y = pk2(x[0][2], x[0][3]); xo.z = pk2(x[1][0], x[1][1]); xo.w = pk2(x[1][2], x[1][3]); *(u32x4*)(X + eo + bj * HALF) = xo; }
;                     if (gnext && live) { const f32x4 a = x[0] * gn[bj][0], b = x[1] * gn[bj][1];
;                         u32x4 w; w.x = pk2(a[0], a[1]); w.y = pk2(a[2], a[3]); w.z = pk2(b[0], b[1]); w.w = pk2(b[2], b[3]);
;                         *(u32x4*)(AN + (size_t)row * D + colb + bj * HALF) = w; } }
;                 s += __shfl_xor(s, 16); s += __shfl_xor(s, 32);
;                 if (fq == 0 && live) ssq[((size_t)u.pn * MT + row) * 4 + wc] = s; }
.Lp5_noan_0_6:
	v_add_u32_e32 v249, 0x10000, v249
	s_waitcnt vmcnt(5)
	v_and_b32_e32 v207, 0xffff0000, v180
	v_lshlrev_b32_e32 v206, 16, v180
	v_and_b32_e32 v209, 0xffff0000, v181
	v_lshlrev_b32_e32 v208, 16, v181
	v_and_b32_e32 v211, 0xffff0000, v182
	v_lshlrev_b32_e32 v210, 16, v182
	v_and_b32_e32 v213, 0xffff0000, v183
	v_lshlrev_b32_e32 v212, 16, v183
	s_waitcnt vmcnt(4)
	v_and_b32_e32 v215, 0xffff0000, v202
	v_lshlrev_b32_e32 v214, 16, v202
	v_and_b32_e32 v217, 0xffff0000, v203
	v_lshlrev_b32_e32 v216, 16, v203
	v_and_b32_e32 v219, 0xffff0000, v204
	v_lshlrev_b32_e32 v218, 16, v204
	v_and_b32_e32 v221, 0xffff0000, v205
	v_lshlrev_b32_e32 v220, 16, v205
	v_pk_fma_f32 v[206:207], v[62:63], v[14:15], v[206:207]
	v_pk_fma_f32 v[208:209], v[64:65], v[16:17], v[208:209]
	v_pk_fma_f32 v[210:211], v[70:71], v[10:11], v[210:211]
	v_pk_fma_f32 v[212:213], v[72:73], v[12:13], v[212:213]
	v_pk_fma_f32 v[214:215], v[74:75], v[6:7], v[214:215]
	v_pk_fma_f32 v[216:217], v[76:77], v[8:9], v[216:217]
	v_pk_fma_f32 v[218:219], v[78:79], v[2:3], v[218:219]
	v_pk_fma_f32 v[220:221], v[80:81], v[4:5], v[220:221]
	v_pk_mul_f32 v[188:189], v[206:207], v[206:207]
	v_pk_fma_f32 v[188:189], v[208:209], v[208:209], v[188:189]
	v_pk_fma_f32 v[188:189], v[210:211], v[210:211], v[188:189]
	v_pk_fma_f32 v[188:189], v[212:213], v[212:213], v[188:189]
	v_pk_fma_f32 v[188:189], v[214:215], v[214:215], v[188:189]
	v_pk_fma_f32 v[188:189], v[216:217], v[216:217], v[188:189]
	v_pk_fma_f32 v[188:189], v[218:219], v[218:219], v[188:189]
	v_pk_fma_f32 v[188:189], v[220:221], v[220:221], v[188:189]
	v_add_f32_e32 v250, v188, v189
	v_cvt_pk_bf16_f32 v222, v206, v207
	v_cvt_pk_bf16_f32 v223, v208, v209
	v_cvt_pk_bf16_f32 v224, v210, v211
	v_cvt_pk_bf16_f32 v225, v212, v213
	global_store_dwordx4 v249, v[222:225], s[40:41]
	v_cvt_pk_bf16_f32 v228, v214, v215
	v_cvt_pk_bf16_f32 v229, v216, v217
	v_cvt_pk_bf16_f32 v230, v218, v219
	v_cvt_pk_bf16_f32 v231, v220, v221
	global_store_dwordx4 v249, v[228:231], s[40:41] offset:256
	s_cmp_eq_u32 s22, 0
	s_cbranch_scc1 .Lp5_noan_0_7
	v_pk_mul_f32 v[206:207], v[206:207], v[82:83]
	v_pk_mul_f32 v[208:209], v[208:209], v[84:85]
	v_pk_mul_f32 v[210:211], v[210:211], v[86:87]
	v_pk_mul_f32 v[212:213], v[212:213], v[88:89]
	v_cvt_pk_bf16_f32 v222, v206, v207
	v_cvt_pk_bf16_f32 v223, v208, v209
	v_cvt_pk_bf16_f32 v224, v210, v211
	v_cvt_pk_bf16_f32 v225, v212, v213
	v_pk_mul_f32 v[214:215], v[214:215], v[90:91]
	v_pk_mul_f32 v[216:217], v[216:217], v[92:93]
	v_pk_mul_f32 v[218:219], v[218:219], v[94:95]
	v_pk_mul_f32 v[220:221], v[220:221], v[96:97]
	v_cvt_pk_bf16_f32 v228, v214, v215
	v_cvt_pk_bf16_f32 v229, v216, v217
	v_cvt_pk_bf16_f32 v230, v218, v219
	v_cvt_pk_bf16_f32 v231, v220, v221
	v_add_u32_e32 v243, 0x4400000, v249
	global_store_dwordx4 v243, v[222:225], s[40:41]
	global_store_dwordx4 v243, v[228:231], s[40:41] offset:256
.Lp5_noan_0_7:
	ds_bpermute_b32 v170, v246, v190
	ds_bpermute_b32 v171, v246, v192
	ds_bpermute_b32 v172, v246, v226
	ds_bpermute_b32 v173, v246, v236
	ds_bpermute_b32 v176, v246, v239
	ds_bpermute_b32 v177, v246, v252
	ds_bpermute_b32 v178, v246, v251
	ds_bpermute_b32 v179, v246, v250
	s_waitcnt lgkmcnt(7)
	v_add_f32_e32 v190, v190, v170
	s_waitcnt lgkmcnt(6)
	v_add_f32_e32 v192, v192, v171
	s_waitcnt lgkmcnt(5)
	v_add_f32_e32 v226, v226, v172
	s_waitcnt lgkmcnt(4)
	v_add_f32_e32 v236, v236, v173
	s_waitcnt lgkmcnt(3)
	v_add_f32_e32 v239, v239, v176
	s_waitcnt lgkmcnt(2)
	v_add_f32_e32 v252, v252, v177
	s_waitcnt lgkmcnt(1)
	v_add_f32_e32 v251, v251, v178
	s_waitcnt lgkmcnt(0)
	v_add_f32_e32 v250, v250, v179
	ds_bpermute_b32 v170, v245, v190
	ds_bpermute_b32 v171, v245, v192
	ds_bpermute_b32 v172, v245, v226
	ds_bpermute_b32 v173, v245, v236
	ds_bpermute_b32 v176, v245, v239
	ds_bpermute_b32 v177, v245, v252
	ds_bpermute_b32 v178, v245, v251
	ds_bpermute_b32 v179, v245, v250
	s_waitcnt lgkmcnt(7)
	v_add_f32_e32 v190, v190, v170
	s_waitcnt lgkmcnt(6)
	v_add_f32_e32 v192, v192, v171
	s_waitcnt lgkmcnt(5)
	v_add_f32_e32 v226, v226, v172
	s_waitcnt lgkmcnt(4)
	v_add_f32_e32 v236, v236, v173
	s_waitcnt lgkmcnt(3)
	v_add_f32_e32 v239, v239, v176
	s_waitcnt lgkmcnt(2)
	v_add_f32_e32 v252, v252, v177
	s_waitcnt lgkmcnt(1)
	v_add_f32_e32 v251, v251, v178
	s_waitcnt lgkmcnt(0)
	v_add_f32_e32 v250, v250, v179
	s_mul_i32 s16, s89, 0x22000
	s_lshr_b32 s4, s73, 3
	s_add_u32 s16, s16, s4
	s_add_u32 s16, s16, 0x6700000
	v_lshl_add_u32 v243, v244, 4, s16
	s_mov_b64 exec, 0xffff
	global_store_dword v243, v190, s[40:41]
	global_store_dword v243, v192, s[40:41] offset:256
	global_store_dword v243, v226, s[40:41] offset:512
	global_store_dword v243, v236, s[40:41] offset:768
	global_store_dword v243, v239, s[40:41] offset:2048
	global_store_dword v243, v252, s[40:41] offset:2304
	global_store_dword v243, v251, s[40:41] offset:2560
	global_store_dword v243, v250, s[40:41] offset:2816
	s_mov_b64 exec, -1
	s_waitcnt lgkmcnt(0)
	v_xor_b32_e32 v152, 16, v201
	v_lshlrev_b32_e32 v152, 2, v152
	v_mov_b32_e32 v153, 64
	v_cndmask_b32_e64 v62, 0, 1, s[50:51]
	v_cmp_ne_u32_e64 s[38:39], 1, v62
	s_and_b64 vcc, exec, s[36:37]
	s_mov_b64 s[36:37], -1
	s_cbranch_vccnz .LBB0_1336
	s_andn2_b64 vcc, exec, s[46:47]
	s_cbranch_vccnz .LBB0_1335
	s_barrier
	s_branch .LBB0_1335
